# up-proj fast epilogue: packed f32 math for centre tap and gelu gating; attention: dropped per-tile negm register copies
# speedup vs baseline: 1.0003x; 1.0003x over previous
; #define SBAR() __builtin_amdgcn_sched_barrier(0)
; #define SLOADB(k0) do { vsB0 = *reinterpret_cast<const bf16x8*>(&Vh[(size_t)((k0) + sr) * LDQ + sc]); vsB1 = *reinterpret_cast<const bf16x8*>(&Vh[(size_t)((k0) + 32 + sr) * LDQ + sc]); \
;     ksB = *reinterpret_cast<const bf16x8*>(&Kh[(size_t)((k0) + kr) * LDQ + kc]); } while (0)
; DI void finishSM(f32x16& p0, f32x16& p1, float alpha, float& l_reg, bf16x8& pa0, bf16x8& pa1, bf16x8& pa2, bf16x8& pa3) {
; #pragma unroll
;     for (int r = 0; r < 16; ++r) p1[r] = __builtin_amdgcn_exp2f(p1[r]);
;     float ps = 0;
; #pragma unroll
;     for (int r = 0; r < 16; ++r) ps += p0[r];
; #pragma unroll
;     for (int r = 0; r < 16; ++r) ps += p1[r];
;     { auto rr = __builtin_amdgcn_permlane32_swap(__float_as_uint(ps), __float_as_uint(ps), false, false);
;       ps = __uint_as_float(rr[0]) + __uint_as_float(rr[1]); }
;     l_reg = l_reg * alpha + ps;
;     ...
;     PK4(p0, 0, pa0); PK4(p0, 8, pa1); PK4(p1, 0, pa2); PK4(p1, 8, pa3);
;     ...
; }
; DI void qkt(f32x16& p0, f32x16& p1, const char* Ks, const bf16x8* qr, const f32x16& negm, int r32, int hi) {
;     { const bf16x8 b0 = *reinterpret_cast<const bf16x8*>(Ks + KSWZ(r32, hi * 16));
;       const bf16x8 b1 = *reinterpret_cast<const bf16x8*>(Ks + KSWZ(32 + r32, hi * 16));
;       p0 = __builtin_amdgcn_mfma_f32_32x32x16_bf16(b0, qr[0], negm, 0, 0, 0);
;       p1 = __builtin_amdgcn_mfma_f32_32x32x16_bf16(b1, qr[0], negm, 0, 0, 0); }
; #pragma unroll
;     for (int d0 = 1; d0 < 4; ++d0) { const int cb = (d0 * 16 + hi * 8) * 2;
;         const bf16x8 b0 = *reinterpret_cast<const bf16x8*>(Ks + KSWZ(r32, cb));
;         const bf16x8 b1 = *reinterpret_cast<const bf16x8*>(Ks + KSWZ(32 + r32, cb));
;         p0 = __builtin_amdgcn_mfma_f32_32x32x16_bf16(b0, qr[d0], p0, 0, 0, 0);
;         p1 = __builtin_amdgcn_mfma_f32_32x32x16_bf16(b1, qr[d0], p1, 0, 0, 0); }
; DI void attn_pass(const bf16_t* __restrict__ Qb, const bf16_t* __restrict__ Kh, const bf16_t* __restrict__ Vh, int seq, char* lds, f32x16 (&o)[4], float& l_out) {
;     ...
;         SBAR(); qkt(pB0, pB1, K_lds + SHM_K, qr, negm, r32, hi);
;         finishSM(pA0, pA1, alA, l_reg, pa0, pa1, pa2, pa3); SBAR();
;         SLOADB((j + 2) * KVBLK); SBAR();
.LBB0_1038:
	ds_read_b128 v[80:83], v217 offset:40960
	ds_read_b128 v[84:87], v217 offset:45056
	v_exp_f32_e32 v88, v96
	v_exp_f32_e32 v89, v97
	v_exp_f32_e32 v90, v98
	s_waitcnt lgkmcnt(1)
	v_mfma_f32_32x32x16_bf16 v[128:143], v[80:83], v[148:151], v[64:79]
	v_exp_f32_e32 v91, v99
	v_exp_f32_e32 v92, v100
	v_exp_f32_e32 v93, v101
	v_exp_f32_e32 v94, v102
	v_exp_f32_e32 v95, v103
	v_exp_f32_e32 v96, v104
	v_exp_f32_e32 v97, v105
	s_waitcnt lgkmcnt(0)
	v_mfma_f32_32x32x16_bf16 v[112:127], v[84:87], v[148:151], v[64:79]
	ds_read_b128 v[80:83], v218 offset:40960
	ds_read_b128 v[84:87], v218 offset:45056
	v_exp_f32_e32 v98, v106
	v_exp_f32_e32 v99, v107
	v_exp_f32_e32 v100, v108
	v_exp_f32_e32 v101, v109
	v_exp_f32_e32 v102, v110
	v_exp_f32_e32 v103, v111
	s_waitcnt lgkmcnt(1)
	v_mfma_f32_32x32x16_bf16 v[128:143], v[80:83], v[144:147], v[128:143]
	s_waitcnt lgkmcnt(0)
	v_mfma_f32_32x32x16_bf16 v[112:127], v[84:87], v[144:147], v[112:127]
	ds_read_b128 v[80:83], v219 offset:40960
	ds_read_b128 v[84:87], v219 offset:45056
	s_waitcnt lgkmcnt(1)
	v_mfma_f32_32x32x16_bf16 v[128:143], v[80:83], v[152:155], v[128:143]
	s_waitcnt lgkmcnt(0)
	v_mfma_f32_32x32x16_bf16 v[112:127], v[84:87], v[152:155], v[112:127]
	ds_read_b128 v[80:83], v216 offset:40960
	ds_read_b128 v[84:87], v216 offset:45056
	s_waitcnt lgkmcnt(1)
	v_mfma_f32_32x32x16_bf16 v[128:143], v[80:83], v[156:159], v[128:143]
	v_add_f32_e32 v80, 0, v207
	v_add_f32_e32 v80, v209, v80
	v_add_f32_e32 v80, v183, v80
	v_add_f32_e32 v80, v208, v80
	v_add_f32_e32 v80, v181, v80
	v_add_f32_e32 v80, v206, v80
	v_add_f32_e32 v80, v180, v80
	v_add_f32_e32 v80, v182, v80
	v_add_f32_e32 v80, v173, v80
	v_add_f32_e32 v80, v175, v80
	v_add_f32_e32 v80, v172, v80
	v_add_f32_e32 v80, v174, v80
	v_add_f32_e32 v80, v177, v80
	v_add_f32_e32 v80, v179, v80
	v_add_f32_e32 v80, v176, v80
	v_add_f32_e32 v80, v178, v80
	v_add_f32_e32 v80, v88, v80
	v_add_f32_e32 v80, v89, v80
	v_add_f32_e32 v80, v90, v80
	v_add_f32_e32 v80, v91, v80
	v_add_f32_e32 v80, v92, v80
	v_add_f32_e32 v80, v93, v80
	v_add_f32_e32 v80, v94, v80
	v_add_f32_e32 v80, v95, v80
	v_add_f32_e32 v80, v96, v80
	v_add_f32_e32 v80, v97, v80
	s_waitcnt lgkmcnt(0)
	v_mfma_f32_32x32x16_bf16 v[112:127], v[84:87], v[156:159], v[112:127]
	v_add_f32_e32 v80, v98, v80
	v_add_f32_e32 v80, v99, v80
	v_add_f32_e32 v80, v100, v80
	v_add_f32_e32 v80, v101, v80
	v_add_f32_e32 v80, v102, v80
	v_add_f32_e32 v222, v103, v80
	v_mov_b32_e32 v223, v222
	v_cvt_pk_bf16_f32 v80, v207, v209
	v_cvt_pk_bf16_f32 v81, v183, v208
	v_cvt_pk_bf16_f32 v82, v181, v206
	s_nop 1
	v_permlane32_swap_b32_e32 v222, v223
	v_cvt_pk_bf16_f32 v83, v180, v182
	v_permlane32_swap_b32_e32 v80, v82
	v_cvt_pk_bf16_f32 v84, v173, v175
	v_cvt_pk_bf16_f32 v85, v172, v174
	v_cvt_pk_bf16_f32 v86, v177, v179
	v_cvt_pk_bf16_f32 v87, v176, v178
	v_cvt_pk_bf16_f32 v88, v88, v89
	v_cvt_pk_bf16_f32 v89, v90, v91
	v_cvt_pk_bf16_f32 v90, v92, v93
	v_cvt_pk_bf16_f32 v91, v94, v95
	v_cvt_pk_bf16_f32 v92, v96, v97
	v_cvt_pk_bf16_f32 v93, v98, v99
	v_cvt_pk_bf16_f32 v94, v100, v101
	v_cvt_pk_bf16_f32 v95, v102, v103
	v_permlane32_swap_b32_e32 v81, v83
	v_permlane32_swap_b32_e32 v84, v86
	v_permlane32_swap_b32_e32 v85, v87
	v_permlane32_swap_b32_e32 v88, v90
	v_permlane32_swap_b32_e32 v89, v91
	v_permlane32_swap_b32_e32 v92, v94
	v_permlane32_swap_b32_e32 v93, v95
	v_lshl_add_u64 v[206:207], v[204:205], 0, s[14:15]
	s_mov_b32 s4, 0x19c60000
	v_add_co_u32_e32 v96, vcc, s4, v206
	s_mov_b32 s4, 0x19c70000
	s_nop 0
	v_addc_co_u32_e32 v97, vcc, 0, v207, vcc
	v_add_co_u32_e32 v98, vcc, s4, v206
	v_lshl_add_u64 v[208:209], v[202:203], 0, s[14:15]
	s_nop 0
	v_addc_co_u32_e32 v99, vcc, 0, v207, vcc
	s_mov_b32 s4, 0x13c60000
	global_load_dwordx4 v[172:175], v[96:97], off
	global_load_dwordx4 v[176:179], v[98:99], off
	v_add_co_u32_e32 v96, vcc, s4, v208
	s_nop 1
	v_addc_co_u32_e32 v97, vcc, 0, v209, vcc
	global_load_dwordx4 v[180:183], v[96:97], off
	ds_read_b64_tr_b16 v[96:97], v220 offset:0
	ds_read_b64_tr_b16 v[98:99], v220 offset:0x800
	ds_read_b64_tr_b16 v[100:101], v220 offset:0x1000
	ds_read_b64_tr_b16 v[102:103], v220 offset:0x1800
	ds_read_b64_tr_b16 v[104:105], v220 offset:0x2000
	ds_read_b64_tr_b16 v[106:107], v220 offset:0x2800
	ds_read_b64_tr_b16 v[108:109], v220 offset:0x3000
	ds_read_b64_tr_b16 v[110:111], v220 offset:0x3800
	s_waitcnt lgkmcnt(0)
; #define SBAR() __builtin_amdgcn_sched_barrier(0)
; template <int OFF> DI s16x4 tr_read(int vb) { s16x4 r; asm volatile("ds_read_b64_tr_b16 %0, %1 offset:%2" : "=&v"(r) : "v"(vb), "i"(OFF) : "memory"); return r; }
; DI void partialSM(f32x16& p0, f32x16& p1, float& m_reg, f32x16& negm, float& alpha) {
;     constexpr float THR2 = THR * 1.4426950408889634f;
;     float pmax = p0[0];
; #pragma unroll
;     for (int r = 1; r < 16; ++r) pmax = fmaxf(pmax, p0[r]);
; #pragma unroll
;     for (int r = 0; r < 16; ++r) pmax = fmaxf(pmax, p1[r]);
;     { auto rr = __builtin_amdgcn_permlane32_swap(__float_as_uint(pmax), __float_as_uint(pmax), false, false);
;       pmax = fmaxf(__uint_as_float(rr[0]), __uint_as_float(rr[1])); }
;     const bool first = m_reg < -1e29f;
;     if (__builtin_expect(__all(!first && pmax <= THR2), 1)) { alpha = 1.f; }
; template <int D0> DI void pv_one(f32x16& od, int vb, bf16x8 pa0, bf16x8 pa1, bf16x8 pa2, bf16x8 pa3) {
;     const s16x4 l0 = tr_read<v_rd_off(D0, 0, 0)>(vb), h0 = tr_read<v_rd_off(D0, 0, 1)>(vb), l1 = tr_read<v_rd_off(D0, 1, 0)>(vb), h1 = tr_read<v_rd_off(D0, 1, 1)>(vb);
;     const s16x4 l2 = tr_read<v_rd_off(D0, 2, 0)>(vb), h2 = tr_read<v_rd_off(D0, 2, 1)>(vb), l3 = tr_read<v_rd_off(D0, 3, 0)>(vb), h3 = tr_read<v_rd_off(D0, 3, 1)>(vb);
;     asm volatile("s_waitcnt lgkmcnt(0)" ::: "memory"); SBAR();
;     ...
;     od = __builtin_amdgcn_mfma_f32_32x32x16_bf16(pa0, PKV(l0, h0), od, 0, 0, 0);
;     od = __builtin_amdgcn_mfma_f32_32x32x16_bf16(pa1, PKV(l1, h1), od, 0, 0, 0);
;     od = __builtin_amdgcn_mfma_f32_32x32x16_bf16(pa2, PKV(l2, h2), od, 0, 0, 0);
;     od = __builtin_amdgcn_mfma_f32_32x32x16_bf16(pa3, PKV(l3, h3), od, 0, 0, 0);
;     ...
; }
; DI void pv_d0(f32x16* o, int vb, bf16x8 pa0, bf16x8 pa1, bf16x8 pa2, bf16x8 pa3) {
;     pv_one<0>(o[0], vb, pa0, pa1, pa2, pa3); pv_one<1>(o[1], vb, pa0, pa1, pa2, pa3); pv_one<2>(o[2], vb, pa0, pa1, pa2, pa3); pv_one<3>(o[3], vb, pa0, pa1, pa2, pa3);
	s_nop 0
	v_mfma_f32_32x32x16_bf16 v[48:63], v[80:83], v[96:99], v[48:63]
	ds_read_b64_tr_b16 v[96:97], v220 offset:0x200
	ds_read_b64_tr_b16 v[98:99], v220 offset:0xa00
	v_mfma_f32_32x32x16_bf16 v[48:63], v[84:87], v[100:103], v[48:63]
	ds_read_b64_tr_b16 v[100:101], v220 offset:0x1200
	ds_read_b64_tr_b16 v[102:103], v220 offset:0x1a00
	v_mfma_f32_32x32x16_bf16 v[48:63], v[88:91], v[104:107], v[48:63]
	ds_read_b64_tr_b16 v[104:105], v220 offset:0x2200
	ds_read_b64_tr_b16 v[106:107], v220 offset:0x2a00
	v_mfma_f32_32x32x16_bf16 v[48:63], v[92:95], v[108:111], v[48:63]
	ds_read_b64_tr_b16 v[108:109], v220 offset:0x3200
	ds_read_b64_tr_b16 v[110:111], v220 offset:0x3a00
	s_waitcnt lgkmcnt(0)
	v_mfma_f32_32x32x16_bf16 v[32:47], v[80:83], v[96:99], v[32:47]
	ds_read_b64_tr_b16 v[96:97], v220 offset:0x400
	ds_read_b64_tr_b16 v[98:99], v220 offset:0xc00
	v_mfma_f32_32x32x16_bf16 v[32:47], v[84:87], v[100:103], v[32:47]
	ds_read_b64_tr_b16 v[100:101], v220 offset:0x1400
	ds_read_b64_tr_b16 v[102:103], v220 offset:0x1c00
	v_mfma_f32_32x32x16_bf16 v[32:47], v[88:91], v[104:107], v[32:47]
	ds_read_b64_tr_b16 v[104:105], v220 offset:0x2400
	ds_read_b64_tr_b16 v[106:107], v220 offset:0x2c00
	v_mfma_f32_32x32x16_bf16 v[32:47], v[92:95], v[108:111], v[32:47]
	ds_read_b64_tr_b16 v[108:109], v220 offset:0x3400
	ds_read_b64_tr_b16 v[110:111], v220 offset:0x3c00
	s_waitcnt lgkmcnt(0)
	v_mfma_f32_32x32x16_bf16 v[16:31], v[80:83], v[96:99], v[16:31]
	ds_read_b64_tr_b16 v[96:97], v220 offset:0x600
	ds_read_b64_tr_b16 v[98:99], v220 offset:0xe00
	v_mfma_f32_32x32x16_bf16 v[16:31], v[84:87], v[100:103], v[16:31]
	ds_read_b64_tr_b16 v[100:101], v220 offset:0x1600
	ds_read_b64_tr_b16 v[102:103], v220 offset:0x1e00
	v_mfma_f32_32x32x16_bf16 v[16:31], v[88:91], v[104:107], v[16:31]
	ds_read_b64_tr_b16 v[104:105], v220 offset:0x2600
	ds_read_b64_tr_b16 v[106:107], v220 offset:0x2e00
	v_mfma_f32_32x32x16_bf16 v[16:31], v[92:95], v[108:111], v[16:31]
	ds_read_b64_tr_b16 v[108:109], v220 offset:0x3600
	ds_read_b64_tr_b16 v[110:111], v220 offset:0x3e00
	s_waitcnt lgkmcnt(0)
	v_mfma_f32_32x32x16_bf16 v[0:15], v[80:83], v[96:99], v[0:15]
	v_max_f32_e32 v80, v129, v129
	v_max_f32_e32 v81, v128, v128
	v_max_f32_e32 v80, v81, v80
	v_max3_f32 v80, v80, v130, v131
	v_max3_f32 v80, v80, v132, v133
	v_max3_f32 v80, v80, v134, v135
	v_max3_f32 v80, v80, v136, v137
	v_mfma_f32_32x32x16_bf16 v[0:15], v[84:87], v[100:103], v[0:15]
	v_max3_f32 v80, v80, v138, v139
	v_max3_f32 v80, v80, v140, v141
	v_max3_f32 v80, v80, v142, v143
	v_max3_f32 v80, v80, v112, v113
	v_max3_f32 v80, v80, v114, v115
	v_max3_f32 v80, v80, v116, v117
	v_max3_f32 v80, v80, v118, v119
	v_mfma_f32_32x32x16_bf16 v[0:15], v[88:91], v[104:107], v[0:15]
	v_max3_f32 v80, v80, v120, v121
	v_max3_f32 v80, v80, v122, v123
	v_max3_f32 v80, v80, v124, v125
	v_max3_f32 v80, v80, v126, v127
	v_mov_b32_e32 v81, v80
	s_nop 1
	v_permlane32_swap_b32_e32 v80, v81
	v_mfma_f32_32x32x16_bf16 v[0:15], v[92:95], v[108:111], v[0:15]
	v_max_f32_e32 v81, v81, v81
	v_max_f32_e32 v80, v80, v80
	v_max_f32_e32 v80, v80, v81
	v_cmp_ngt_f32_e32 vcc, s83, v200
	v_cmp_ge_f32_e64 s[8:9], s63, v80
	s_and_b64 s[4:5], vcc, s[8:9]
	v_cndmask_b32_e64 v81, 0, 1, s[4:5]
	v_cmp_ne_u32_e64 s[8:9], 0, v81
	s_cmp_eq_u64 s[8:9], exec
	s_cbranch_scc0 .LBB0_1057
	v_mov_b32_e32 v224, 1.0

; #define SBAR() __builtin_amdgcn_sched_barrier(0)
; #define SLOADA(k0) do { vsA0 = *reinterpret_cast<const bf16x8*>(&Vh[(size_t)((k0) + sr) * LDQ + sc]); vsA1 = *reinterpret_cast<const bf16x8*>(&Vh[(size_t)((k0) + 32 + sr) * LDQ + sc]); \
;     ksA = *reinterpret_cast<const bf16x8*>(&Kh[(size_t)((k0) + kr) * LDQ + kc]); } while (0)
; DI void finishSM(f32x16& p0, f32x16& p1, float alpha, float& l_reg, bf16x8& pa0, bf16x8& pa1, bf16x8& pa2, bf16x8& pa3) {
; #pragma unroll
;     for (int r = 0; r < 16; ++r) p1[r] = __builtin_amdgcn_exp2f(p1[r]);
;     float ps = 0;
; #pragma unroll
;     for (int r = 0; r < 16; ++r) ps += p0[r];
; #pragma unroll
;     for (int r = 0; r < 16; ++r) ps += p1[r];
;     { auto rr = __builtin_amdgcn_permlane32_swap(__float_as_uint(ps), __float_as_uint(ps), false, false);
;       ps = __uint_as_float(rr[0]) + __uint_as_float(rr[1]); }
;     l_reg = l_reg * alpha + ps;
;     ...
;     PK4(p0, 0, pa0); PK4(p0, 8, pa1); PK4(p1, 0, pa2); PK4(p1, 8, pa3);
;     ...
; }
; DI void qkt(f32x16& p0, f32x16& p1, const char* Ks, const bf16x8* qr, const f32x16& negm, int r32, int hi) {
;     { const bf16x8 b0 = *reinterpret_cast<const bf16x8*>(Ks + KSWZ(r32, hi * 16));
;       const bf16x8 b1 = *reinterpret_cast<const bf16x8*>(Ks + KSWZ(32 + r32, hi * 16));
;       p0 = __builtin_amdgcn_mfma_f32_32x32x16_bf16(b0, qr[0], negm, 0, 0, 0);
;       p1 = __builtin_amdgcn_mfma_f32_32x32x16_bf16(b1, qr[0], negm, 0, 0, 0); }
; #pragma unroll
;     for (int d0 = 1; d0 < 4; ++d0) { const int cb = (d0 * 16 + hi * 8) * 2;
;         const bf16x8 b0 = *reinterpret_cast<const bf16x8*>(Ks + KSWZ(r32, cb));
;         const bf16x8 b1 = *reinterpret_cast<const bf16x8*>(Ks + KSWZ(32 + r32, cb));
;         p0 = __builtin_amdgcn_mfma_f32_32x32x16_bf16(b0, qr[d0], p0, 0, 0, 0);
;         p1 = __builtin_amdgcn_mfma_f32_32x32x16_bf16(b1, qr[d0], p1, 0, 0, 0); }
; DI void attn_pass(const bf16_t* __restrict__ Qb, const bf16_t* __restrict__ Kh, const bf16_t* __restrict__ Vh, int seq, char* lds, f32x16 (&o)[4], float& l_out) {
;     ...
;         SBAR(); qkt(pA0, pA1, K_lds, qr, negm, r32, hi);
;         finishSM(pB0, pB1, alB, l_reg, pa0, pa1, pa2, pa3); SBAR();
;         if (j + 3 < NT) SLOADA((j + 3) * KVBLK); SBAR();
.LBB0_1044:
	v_exp_f32_e32 v246, v128
	v_exp_f32_e32 v248, v129
	v_exp_f32_e32 v244, v130
	v_exp_f32_e32 v247, v131
	v_exp_f32_e32 v236, v132
	v_exp_f32_e32 v245, v133
	v_exp_f32_e32 v235, v134
	v_exp_f32_e32 v237, v135
	v_exp_f32_e32 v232, v136
	v_exp_f32_e32 v234, v137
	v_exp_f32_e32 v230, v138
	v_exp_f32_e32 v233, v139
	v_exp_f32_e32 v228, v140
	v_exp_f32_e32 v231, v141
	v_exp_f32_e32 v227, v142
	v_exp_f32_e32 v229, v143
	s_waitcnt lgkmcnt(0)
	s_barrier
	ds_read_b128 v[96:99], v217 offset:32768
	ds_read_b128 v[250:253], v217 offset:36864
	v_exp_f32_e32 v249, v120
	v_exp_f32_e32 v254, v121
	v_exp_f32_e32 v186, v122
	s_waitcnt lgkmcnt(1)
	v_mfma_f32_32x32x16_bf16 v[128:143], v[96:99], v[148:151], v[64:79]
	v_exp_f32_e32 v187, v123
	v_exp_f32_e32 v188, v124
	v_exp_f32_e32 v189, v125
	v_exp_f32_e32 v194, v126
	v_exp_f32_e32 v127, v127
	s_waitcnt lgkmcnt(0)
	v_mfma_f32_32x32x16_bf16 v[96:111], v[250:253], v[148:151], v[64:79]
	ds_read_b128 v[250:253], v218 offset:32768
	ds_read_b128 v[238:241], v218 offset:36864
	s_waitcnt lgkmcnt(1)
	v_mfma_f32_32x32x16_bf16 v[128:143], v[250:253], v[144:147], v[128:143]
	s_waitcnt lgkmcnt(0)
	v_mfma_f32_32x32x16_bf16 v[96:111], v[238:241], v[144:147], v[96:111]
	ds_read_b128 v[238:241], v219 offset:32768
	ds_read_b128 v[250:253], v219 offset:36864
	s_waitcnt lgkmcnt(1)
	v_mfma_f32_32x32x16_bf16 v[128:143], v[238:241], v[152:155], v[128:143]
	s_waitcnt lgkmcnt(0)
	v_mfma_f32_32x32x16_bf16 v[96:111], v[250:253], v[152:155], v[96:111]
	ds_read_b128 v[238:241], v216 offset:32768
	ds_read_b128 v[250:253], v216 offset:36864
	s_waitcnt lgkmcnt(1)
	v_mfma_f32_32x32x16_bf16 v[128:143], v[238:241], v[156:159], v[128:143]
	v_exp_f32_e32 v238, v112
	v_add_f32_e32 v112, 0, v246
	v_add_f32_e32 v112, v248, v112
	v_add_f32_e32 v112, v244, v112
	v_add_f32_e32 v112, v247, v112
	v_add_f32_e32 v112, v236, v112
	v_add_f32_e32 v112, v245, v112
	v_add_f32_e32 v112, v235, v112
	v_add_f32_e32 v112, v237, v112
	v_add_f32_e32 v112, v232, v112
	v_add_f32_e32 v112, v234, v112
	v_add_f32_e32 v112, v230, v112
	v_add_f32_e32 v112, v233, v112
	v_add_f32_e32 v112, v228, v112
	v_exp_f32_e32 v239, v113
	v_add_f32_e32 v112, v231, v112
	v_exp_f32_e32 v240, v114
	v_add_f32_e32 v112, v227, v112
	v_exp_f32_e32 v241, v115
	v_add_f32_e32 v112, v229, v112
	s_waitcnt lgkmcnt(0)
	v_mfma_f32_32x32x16_bf16 v[96:111], v[250:253], v[156:159], v[96:111]
	v_exp_f32_e32 v250, v116
	v_add_f32_e32 v112, v238, v112
	v_exp_f32_e32 v251, v117
	v_add_f32_e32 v112, v239, v112
	v_exp_f32_e32 v252, v118
	v_add_f32_e32 v112, v240, v112
	v_exp_f32_e32 v253, v119
	v_add_f32_e32 v112, v241, v112
	v_add_f32_e32 v112, v250, v112
	v_add_f32_e32 v112, v251, v112
	v_add_f32_e32 v112, v252, v112
	v_add_f32_e32 v112, v253, v112
	v_add_f32_e32 v112, v249, v112
	v_add_f32_e32 v112, v254, v112
	v_add_f32_e32 v112, v186, v112
	v_add_f32_e32 v112, v187, v112
	v_add_f32_e32 v112, v188, v112
	v_add_f32_e32 v112, v189, v112
	v_add_f32_e32 v112, v194, v112
	v_add_f32_e32 v225, v127, v112
	v_mov_b32_e32 v226, v225
	v_cvt_pk_bf16_f32 v112, v246, v248
	v_cvt_pk_bf16_f32 v113, v244, v247
	v_cvt_pk_bf16_f32 v114, v236, v245
	v_cvt_pk_bf16_f32 v115, v235, v237
	v_cvt_pk_bf16_f32 v116, v232, v234
	v_cvt_pk_bf16_f32 v117, v230, v233
	v_cvt_pk_bf16_f32 v118, v228, v231
	v_cvt_pk_bf16_f32 v119, v227, v229
	v_cvt_pk_bf16_f32 v120, v238, v239
	v_cvt_pk_bf16_f32 v121, v240, v241
	v_cvt_pk_bf16_f32 v122, v250, v251
	v_cvt_pk_bf16_f32 v123, v252, v253
	v_cvt_pk_bf16_f32 v124, v249, v254
	v_cvt_pk_bf16_f32 v125, v186, v187
	v_cvt_pk_bf16_f32 v126, v188, v189
	v_cvt_pk_bf16_f32 v127, v194, v127
	s_nop 1
	v_permlane32_swap_b32_e32 v225, v226
	v_permlane32_swap_b32_e32 v112, v114
	v_permlane32_swap_b32_e32 v113, v115
	v_permlane32_swap_b32_e32 v116, v118
	v_permlane32_swap_b32_e32 v117, v119
	v_permlane32_swap_b32_e32 v120, v122
	v_permlane32_swap_b32_e32 v121, v123
	v_permlane32_swap_b32_e32 v124, v126
	v_permlane32_swap_b32_e32 v125, v127
	s_cmp_ge_u32 s2, s22
	s_cselect_b64 s[4:5], -1, 0
	s_and_b64 vcc, exec, s[4:5]
	s_cbranch_vccnz .LBB0_1046
	v_add_co_u32_e32 v160, vcc, 0x19c80000, v206
	s_nop 1
	v_addc_co_u32_e32 v161, vcc, 0, v207, vcc
	v_add_co_u32_e32 v164, vcc, 0x19c90000, v206
	s_nop 1
	v_addc_co_u32_e32 v165, vcc, 0, v207, vcc
	v_add_co_u32_e32 v168, vcc, 0x13c80000, v208
	global_load_dwordx4 v[160:163], v[160:161], off
	s_nop 0
	global_load_dwordx4 v[164:167], v[164:165], off
	v_addc_co_u32_e32 v169, vcc, 0, v209, vcc
	global_load_dwordx4 v[168:171], v[168:169], off

; #define SBAR() __builtin_amdgcn_sched_barrier(0)
; DI void finishSM(f32x16& p0, f32x16& p1, float alpha, float& l_reg, bf16x8& pa0, bf16x8& pa1, bf16x8& pa2, bf16x8& pa3) {
; #pragma unroll
;     for (int r = 0; r < 16; ++r) p1[r] = __builtin_amdgcn_exp2f(p1[r]);
;     float ps = 0;
; #pragma unroll
;     for (int r = 0; r < 16; ++r) ps += p0[r];
; #pragma unroll
;     for (int r = 0; r < 16; ++r) ps += p1[r];
;     { auto rr = __builtin_amdgcn_permlane32_swap(__float_as_uint(ps), __float_as_uint(ps), false, false);
;       ps = __uint_as_float(rr[0]) + __uint_as_float(rr[1]); }
;     l_reg = l_reg * alpha + ps;
;     ...
;     PK4(p0, 0, pa0); PK4(p0, 8, pa1); PK4(p1, 0, pa2); PK4(p1, 8, pa3);
;     ...
; }
; DI void qkt(f32x16& p0, f32x16& p1, const char* Ks, const bf16x8* qr, const f32x16& negm, int r32, int hi) {
;     { const bf16x8 b0 = *reinterpret_cast<const bf16x8*>(Ks + KSWZ(r32, hi * 16));
;       const bf16x8 b1 = *reinterpret_cast<const bf16x8*>(Ks + KSWZ(32 + r32, hi * 16));
;       p0 = __builtin_amdgcn_mfma_f32_32x32x16_bf16(b0, qr[0], negm, 0, 0, 0);
;       p1 = __builtin_amdgcn_mfma_f32_32x32x16_bf16(b1, qr[0], negm, 0, 0, 0); }
; #pragma unroll
;     for (int d0 = 1; d0 < 4; ++d0) { const int cb = (d0 * 16 + hi * 8) * 2;
;         const bf16x8 b0 = *reinterpret_cast<const bf16x8*>(Ks + KSWZ(r32, cb));
;         const bf16x8 b1 = *reinterpret_cast<const bf16x8*>(Ks + KSWZ(32 + r32, cb));
;         p0 = __builtin_amdgcn_mfma_f32_32x32x16_bf16(b0, qr[d0], p0, 0, 0, 0);
;         p1 = __builtin_amdgcn_mfma_f32_32x32x16_bf16(b1, qr[d0], p1, 0, 0, 0); }
; DI void attn_pass(const bf16_t* __restrict__ Qb, const bf16_t* __restrict__ Kh, const bf16_t* __restrict__ Vh, int seq, char* lds, f32x16 (&o)[4], float& l_out) {
;     ...
;     SBAR(); qkt(pB0, pB1, K_lds + SHM_K, qr, negm, r32, hi);
;     finishSM(pA0, pA1, alA, l_reg, pa0, pa1, pa2, pa3); SBAR();
.LBB0_1059:
	v_mov_b64_e32 v[94:95], v[78:79]
	v_mov_b64_e32 v[92:93], v[76:77]
	v_mov_b64_e32 v[90:91], v[74:75]
	v_mov_b64_e32 v[88:89], v[72:73]
	v_mov_b64_e32 v[86:87], v[70:71]
	v_mov_b64_e32 v[84:85], v[68:69]
	v_mov_b64_e32 v[82:83], v[66:67]
	v_mov_b64_e32 v[80:81], v[64:65]
	ds_read_b128 v[114:117], v217 offset:40960
	ds_read_b128 v[118:121], v217 offset:45056
	v_exp_f32_e32 v113, v97
	v_add_f32_e32 v97, 0, v207
	v_add_f32_e32 v97, v209, v97
	s_waitcnt lgkmcnt(1)
	v_mfma_f32_32x32x16_bf16 v[64:79], v[114:117], v[148:151], v[80:95]
	v_add_f32_e32 v97, v183, v97
	v_add_f32_e32 v97, v208, v97
	v_add_f32_e32 v97, v181, v97
	v_add_f32_e32 v97, v206, v97
	v_add_f32_e32 v97, v180, v97
	v_add_f32_e32 v97, v182, v97
	v_add_f32_e32 v97, v173, v97
	s_waitcnt lgkmcnt(0)
	v_mfma_f32_32x32x16_bf16 v[80:95], v[118:121], v[148:151], v[80:95]
	ds_read_b128 v[114:117], v218 offset:40960
	ds_read_b128 v[118:121], v218 offset:45056
	v_add_f32_e32 v97, v175, v97
	v_add_f32_e32 v97, v172, v97
	v_add_f32_e32 v97, v174, v97
	v_exp_f32_e32 v96, v96
	v_add_f32_e32 v97, v177, v97
	v_add_f32_e32 v97, v179, v97
	s_waitcnt lgkmcnt(1)
	v_mfma_f32_32x32x16_bf16 v[64:79], v[114:117], v[144:147], v[64:79]
	v_add_f32_e32 v97, v176, v97
	v_exp_f32_e32 v99, v99
	v_add_f32_e32 v97, v178, v97
	v_add_f32_e32 v97, v96, v97
	v_add_f32_e32 v97, v113, v97
	v_exp_f32_e32 v122, v107
	v_exp_f32_e32 v123, v108
	s_waitcnt lgkmcnt(0)
	v_mfma_f32_32x32x16_bf16 v[80:95], v[118:121], v[144:147], v[80:95]
	ds_read_b128 v[114:117], v219 offset:40960
	ds_read_b128 v[118:121], v219 offset:45056
	v_exp_f32_e32 v124, v109
	v_exp_f32_e32 v125, v110
	v_exp_f32_e32 v126, v111
	s_waitcnt lgkmcnt(1)
	v_mfma_f32_32x32x16_bf16 v[64:79], v[114:117], v[152:155], v[64:79]
	s_waitcnt lgkmcnt(0)
	v_mfma_f32_32x32x16_bf16 v[80:95], v[118:121], v[152:155], v[80:95]
	ds_read_b128 v[114:117], v216 offset:40960
	ds_read_b128 v[118:121], v216 offset:45056
	s_waitcnt lgkmcnt(1)
	v_mfma_f32_32x32x16_bf16 v[64:79], v[114:117], v[156:159], v[64:79]
	v_exp_f32_e32 v114, v98
	v_exp_f32_e32 v115, v100
	v_exp_f32_e32 v116, v101
	v_exp_f32_e32 v117, v102
	v_add_f32_e32 v97, v114, v97
	v_add_f32_e32 v97, v99, v97
	v_add_f32_e32 v97, v115, v97
	s_waitcnt lgkmcnt(0)
	v_mfma_f32_32x32x16_bf16 v[80:95], v[118:121], v[156:159], v[80:95]
	v_exp_f32_e32 v118, v103
	v_exp_f32_e32 v119, v104
	v_exp_f32_e32 v120, v105
	v_add_f32_e32 v97, v116, v97
	v_exp_f32_e32 v121, v106
	v_add_f32_e32 v97, v117, v97
	v_add_f32_e32 v97, v118, v97
	v_add_f32_e32 v97, v119, v97
	v_add_f32_e32 v97, v120, v97
	v_add_f32_e32 v97, v121, v97
	v_add_f32_e32 v97, v122, v97
	v_add_f32_e32 v97, v123, v97
	v_add_f32_e32 v97, v124, v97
	v_add_f32_e32 v97, v125, v97
	v_add_f32_e32 v97, v126, v97
	v_mov_b32_e32 v98, v97
	s_nop 1
	v_permlane32_swap_b32_e32 v97, v98
	v_cvt_pk_bf16_f32 v100, v207, v209
	v_cvt_pk_bf16_f32 v101, v183, v208
	v_cvt_pk_bf16_f32 v102, v181, v206
	v_cvt_pk_bf16_f32 v103, v180, v182
	v_cvt_pk_bf16_f32 v104, v173, v175
	v_cvt_pk_bf16_f32 v105, v172, v174
	v_cvt_pk_bf16_f32 v106, v177, v179
	v_cvt_pk_bf16_f32 v107, v176, v178
	v_cvt_pk_bf16_f32 v108, v96, v113
	v_cvt_pk_bf16_f32 v109, v114, v99
	v_cvt_pk_bf16_f32 v110, v115, v116
	v_cvt_pk_bf16_f32 v111, v117, v118
	v_cvt_pk_bf16_f32 v114, v119, v120
	v_cvt_pk_bf16_f32 v115, v121, v122
	v_cvt_pk_bf16_f32 v116, v123, v124
	v_cvt_pk_bf16_f32 v117, v125, v126
	s_nop 0
	v_permlane32_swap_b32_e32 v100, v102
	v_permlane32_swap_b32_e32 v101, v103
	v_permlane32_swap_b32_e32 v104, v106
	v_permlane32_swap_b32_e32 v105, v107
	v_permlane32_swap_b32_e32 v108, v110
	v_permlane32_swap_b32_e32 v109, v111
	v_permlane32_swap_b32_e32 v114, v116
	v_permlane32_swap_b32_e32 v115, v117
	ds_read_b64_tr_b16 v[118:119], v220 offset:0
	ds_read_b64_tr_b16 v[120:121], v220 offset:0x800
	ds_read_b64_tr_b16 v[122:123], v220 offset:0x1000
	ds_read_b64_tr_b16 v[124:125], v220 offset:0x1800
	ds_read_b64_tr_b16 v[126:127], v220 offset:0x2000
	ds_read_b64_tr_b16 v[128:129], v220 offset:0x2800
	ds_read_b64_tr_b16 v[130:131], v220 offset:0x3000
	ds_read_b64_tr_b16 v[132:133], v220 offset:0x3800
	s_waitcnt lgkmcnt(0)
; #define SBAR() __builtin_amdgcn_sched_barrier(0)
; template <int OFF> DI s16x4 tr_read(int vb) { s16x4 r; asm volatile("ds_read_b64_tr_b16 %0, %1 offset:%2" : "=&v"(r) : "v"(vb), "i"(OFF) : "memory"); return r; }
; DI void partialSM(f32x16& p0, f32x16& p1, float& m_reg, f32x16& negm, float& alpha) {
;     constexpr float THR2 = THR * 1.4426950408889634f;
;     float pmax = p0[0];
; #pragma unroll
;     for (int r = 1; r < 16; ++r) pmax = fmaxf(pmax, p0[r]);
; #pragma unroll
;     for (int r = 0; r < 16; ++r) pmax = fmaxf(pmax, p1[r]);
;     { auto rr = __builtin_amdgcn_permlane32_swap(__float_as_uint(pmax), __float_as_uint(pmax), false, false);
;       pmax = fmaxf(__uint_as_float(rr[0]), __uint_as_float(rr[1])); }
;     const bool first = m_reg < -1e29f;
;     if (__builtin_expect(__all(!first && pmax <= THR2), 1)) { alpha = 1.f; }
; template <int D0> DI void pv_one(f32x16& od, int vb, bf16x8 pa0, bf16x8 pa1, bf16x8 pa2, bf16x8 pa3) {
;     const s16x4 l0 = tr_read<v_rd_off(D0, 0, 0)>(vb), h0 = tr_read<v_rd_off(D0, 0, 1)>(vb), l1 = tr_read<v_rd_off(D0, 1, 0)>(vb), h1 = tr_read<v_rd_off(D0, 1, 1)>(vb);
;     const s16x4 l2 = tr_read<v_rd_off(D0, 2, 0)>(vb), h2 = tr_read<v_rd_off(D0, 2, 1)>(vb), l3 = tr_read<v_rd_off(D0, 3, 0)>(vb), h3 = tr_read<v_rd_off(D0, 3, 1)>(vb);
;     asm volatile("s_waitcnt lgkmcnt(0)" ::: "memory"); SBAR();
;     ...
;     od = __builtin_amdgcn_mfma_f32_32x32x16_bf16(pa0, PKV(l0, h0), od, 0, 0, 0);
;     od = __builtin_amdgcn_mfma_f32_32x32x16_bf16(pa1, PKV(l1, h1), od, 0, 0, 0);
;     od = __builtin_amdgcn_mfma_f32_32x32x16_bf16(pa2, PKV(l2, h2), od, 0, 0, 0);
;     od = __builtin_amdgcn_mfma_f32_32x32x16_bf16(pa3, PKV(l3, h3), od, 0, 0, 0);
;     ...
; }
; DI void pv_d0(f32x16* o, int vb, bf16x8 pa0, bf16x8 pa1, bf16x8 pa2, bf16x8 pa3) {
;     pv_one<0>(o[0], vb, pa0, pa1, pa2, pa3); pv_one<1>(o[1], vb, pa0, pa1, pa2, pa3); pv_one<2>(o[2], vb, pa0, pa1, pa2, pa3); pv_one<3>(o[3], vb, pa0, pa1, pa2, pa3);
	s_nop 0
	v_mfma_f32_32x32x16_bf16 v[48:63], v[100:103], v[118:121], v[48:63]
	ds_read_b64_tr_b16 v[118:119], v220 offset:0x200
	ds_read_b64_tr_b16 v[120:121], v220 offset:0xa00
	v_mfma_f32_32x32x16_bf16 v[48:63], v[104:107], v[122:125], v[48:63]
	ds_read_b64_tr_b16 v[122:123], v220 offset:0x1200
	ds_read_b64_tr_b16 v[124:125], v220 offset:0x1a00
	v_mfma_f32_32x32x16_bf16 v[48:63], v[108:111], v[126:129], v[48:63]
	ds_read_b64_tr_b16 v[126:127], v220 offset:0x2200
	ds_read_b64_tr_b16 v[128:129], v220 offset:0x2a00
	v_mfma_f32_32x32x16_bf16 v[48:63], v[114:117], v[130:133], v[48:63]
	ds_read_b64_tr_b16 v[130:131], v220 offset:0x3200
	ds_read_b64_tr_b16 v[132:133], v220 offset:0x3a00
	s_waitcnt lgkmcnt(0)
	v_mfma_f32_32x32x16_bf16 v[32:47], v[100:103], v[118:121], v[32:47]
	ds_read_b64_tr_b16 v[118:119], v220 offset:0x400
	ds_read_b64_tr_b16 v[120:121], v220 offset:0xc00
	v_mfma_f32_32x32x16_bf16 v[32:47], v[104:107], v[122:125], v[32:47]
	ds_read_b64_tr_b16 v[122:123], v220 offset:0x1400
	ds_read_b64_tr_b16 v[124:125], v220 offset:0x1c00
	v_mfma_f32_32x32x16_bf16 v[32:47], v[108:111], v[126:129], v[32:47]
	ds_read_b64_tr_b16 v[126:127], v220 offset:0x2400
	ds_read_b64_tr_b16 v[128:129], v220 offset:0x2c00
	v_mfma_f32_32x32x16_bf16 v[32:47], v[114:117], v[130:133], v[32:47]
	ds_read_b64_tr_b16 v[130:131], v220 offset:0x3400
	ds_read_b64_tr_b16 v[132:133], v220 offset:0x3c00
	s_waitcnt lgkmcnt(0)
	v_mfma_f32_32x32x16_bf16 v[16:31], v[100:103], v[118:121], v[16:31]
	ds_read_b64_tr_b16 v[118:119], v220 offset:0x600
	ds_read_b64_tr_b16 v[120:121], v220 offset:0xe00
	v_mfma_f32_32x32x16_bf16 v[16:31], v[104:107], v[122:125], v[16:31]
	ds_read_b64_tr_b16 v[122:123], v220 offset:0x1600
	ds_read_b64_tr_b16 v[124:125], v220 offset:0x1e00
	v_mfma_f32_32x32x16_bf16 v[16:31], v[108:111], v[126:129], v[16:31]
	ds_read_b64_tr_b16 v[126:127], v220 offset:0x2600
	ds_read_b64_tr_b16 v[128:129], v220 offset:0x2e00
	v_mfma_f32_32x32x16_bf16 v[16:31], v[114:117], v[130:133], v[16:31]
	ds_read_b64_tr_b16 v[130:131], v220 offset:0x3600
	ds_read_b64_tr_b16 v[132:133], v220 offset:0x3e00
	s_waitcnt lgkmcnt(0)
	v_mfma_f32_32x32x16_bf16 v[0:15], v[100:103], v[118:121], v[0:15]
	v_max_f32_e32 v96, v65, v65
	v_max_f32_e32 v99, v64, v64
	v_max_f32_e32 v96, v99, v96
	v_max3_f32 v96, v96, v66, v67
	v_max3_f32 v96, v96, v68, v69
	v_max3_f32 v96, v96, v70, v71
	v_max3_f32 v96, v96, v72, v73
	v_mfma_f32_32x32x16_bf16 v[0:15], v[104:107], v[122:125], v[0:15]
	v_max3_f32 v96, v96, v74, v75
	v_max3_f32 v96, v96, v76, v77
	v_max3_f32 v96, v96, v78, v79
	v_max3_f32 v96, v96, v80, v81
	v_max3_f32 v96, v96, v82, v83
	v_max3_f32 v96, v96, v84, v85
	v_max3_f32 v96, v96, v86, v87
	v_mfma_f32_32x32x16_bf16 v[0:15], v[108:111], v[126:129], v[0:15]
	v_max3_f32 v96, v96, v88, v89
	v_max3_f32 v96, v96, v90, v91
	v_max3_f32 v96, v96, v92, v93
	v_max3_f32 v96, v96, v94, v95
	v_mov_b32_e32 v99, v96
	s_nop 1
	v_permlane32_swap_b32_e32 v96, v99
	v_mfma_f32_32x32x16_bf16 v[0:15], v[114:117], v[130:133], v[0:15]
	v_max_f32_e32 v99, v99, v99
	v_max_f32_e32 v96, v96, v96
	v_max_f32_e32 v96, v96, v99
	v_cmp_ngt_f32_e32 vcc, s83, v200
	v_cmp_ge_f32_e64 s[8:9], s63, v96
	s_and_b64 s[4:5], vcc, s[8:9]
	v_cndmask_b32_e64 v99, 0, 1, s[4:5]
	v_cmp_ne_u32_e64 s[8:9], 0, v99
	v_mov_b32_e32 v99, 1.0
	s_cmp_eq_u64 s[8:9], exec
	s_cbranch_scc0 .LBB0_1071

;     DI void operator()(const f32x4 (&acc)[2][2][4][2], const Unit& u, int wr, int wc, int fr_, int fq_) const {
;         int fr = fr_, fq = fq_; asm volatile("" : "+v"(fr), "+v"(fq));
;         const int lane = fr | (fq << 4);
;         const int src_up = (lane & 48) | ((fr + 15) & 15), src_dn = (lane & 48) | ((fr + 1) & 15);
;         const int cv0 = u.pn * 128 + wc * 32 + 8 * fq;
; #pragma unroll
;         for (int n = 0; n < 2; ++n) {
;             const int sv = cv0 + 4 * n, sg = FF + cv0 + 4 * n;
;             const f32x4 vp = *(const f32x4*)(cw + sv), vm = *(const f32x4*)(cw + NUP + sv), vn = *(const f32x4*)(cw + 2 * NUP + sv), vb = *(const f32x4*)(cb + sv);
;             const f32x4 gp = *(const f32x4*)(cw + sg), gm = *(const f32x4*)(cw + NUP + sg), gn = *(const f32x4*)(cw + 2 * NUP + sg), gb = *(const f32x4*)(cb + sg);
; #pragma unroll
;             for (int ai = 0; ai < 2; ++ai) {
;                 const int tok0 = u.pm * 248 + (2 * ai + wr) * 62 - 1;
; #pragma unroll
;                 for (int m = 0; m < 4; ++m) { f32x4 zv, zg;
;                     CONV_ONE(acc, ai, 0, n, m, zv, vp, vm, vn); CONV_ONE(acc, ai, 1, n, m, zg, gp, gm, gn);
;                     zv = zv + vb; zg = zg + gb;
.LBB0_1268:
	s_mul_i32 s98, s16, 0xf8
	s_add_i32 s99, s98, -1
	s_add_i32 s100, s98, 0xf8
	s_ashr_i32 s99, s99, 12
	s_ashr_i32 s100, s100, 12
	s_cmp_lg_u32 s99, s100
	s_cbranch_scc1 .Lup_slow
	s_mov_b64 s[28:29], exec
	v_readlane_b32 s9, v255, 18
	v_readlane_b32 s18, v255, 14
	v_readlane_b32 s19, v255, 15
	v_readlane_b32 s20, v255, 16
	v_readlane_b32 s21, v255, 17
	v_readlane_b32 s22, v255, 22
	s_lshl_b32 s8, s4, 7
	v_cmp_eq_u32_e64 s[10:11], 0, v180
	v_cmp_eq_u32_e64 s[12:13], 15, v180
	v_cmp_ne_u32_e64 s[14:15], 0, v180
	v_cmp_ne_u32_e64 s[24:25], 15, v180
	s_or_b32 s8, s8, s9
	s_add_i32 s22, s22, s98
	v_lshl_add_u32 v170, v181, 3, s8
	v_add_u32_e32 v186, s22, v180
	v_lshlrev_b32_e32 v188, 2, v170
	v_add_u32_e32 v186, -1, v186
	v_add_u32_e32 v189, 0x2c00, v188
	v_mul_u32_u24_e32 v186, 0x1600, v186
	v_lshl_add_u32 v186, v170, 1, v186
	v_mov_b32_e32 v187, 0
	s_mov_b32 s27, 0
	s_mov_b32 s40, 0x3d372713
	s_mov_b32 s42, 0xc0135761
	s_mov_b32 s44, 1.0
	v_lshl_add_u64 v[186:187], v[186:187], 0, s[84:85]
	global_load_dwordx4 v[96:99], v188, s[18:19] offset:0
	global_load_dwordx4 v[100:103], v188, s[88:89] offset:0
	global_load_dwordx4 v[104:107], v188, s[90:91] offset:0
	global_load_dwordx4 v[108:111], v188, s[20:21] offset:0
	global_load_dwordx4 v[112:115], v189, s[18:19] offset:0
	global_load_dwordx4 v[116:119], v189, s[88:89] offset:0
	global_load_dwordx4 v[120:123], v189, s[90:91] offset:0
	global_load_dwordx4 v[124:127], v189, s[20:21] offset:0
	s_waitcnt vmcnt(0)
	v_cndmask_b32_e64 v200, 0, v96, s[10:11]
	v_cndmask_b32_e64 v204, 0, v104, s[12:13]
	v_cndmask_b32_e64 v208, 0, v112, s[10:11]
	v_cndmask_b32_e64 v212, 0, v120, s[12:13]
	v_cndmask_b32_e64 v201, 0, v97, s[10:11]
	v_cndmask_b32_e64 v205, 0, v105, s[12:13]
	v_cndmask_b32_e64 v209, 0, v113, s[10:11]
	v_cndmask_b32_e64 v213, 0, v121, s[12:13]
	v_cndmask_b32_e64 v202, 0, v98, s[10:11]
	v_cndmask_b32_e64 v206, 0, v106, s[12:13]
	v_cndmask_b32_e64 v210, 0, v114, s[10:11]
	v_cndmask_b32_e64 v214, 0, v122, s[12:13]
	v_cndmask_b32_e64 v203, 0, v99, s[10:11]
	v_cndmask_b32_e64 v207, 0, v107, s[12:13]
	v_cndmask_b32_e64 v211, 0, v115, s[10:11]
	v_cndmask_b32_e64 v215, 0, v123, s[12:13]
	v_pk_fma_f32 v[216:217], v[156:157], v[100:101], v[108:109]
	v_pk_fma_f32 v[218:219], v[148:149], v[100:101], v[108:109]
	v_pk_fma_f32 v[220:221], v[158:159], v[102:103], v[110:111]
	v_pk_fma_f32 v[222:223], v[150:151], v[102:103], v[110:111]
	v_pk_fma_f32 v[224:225], v[152:153], v[116:117], v[124:125]
	v_pk_fma_f32 v[226:227], v[144:145], v[116:117], v[124:125]
	v_pk_fma_f32 v[228:229], v[154:155], v[118:119], v[126:127]
	v_pk_fma_f32 v[194:195], v[146:147], v[118:119], v[126:127]
	v_fmac_f32_dpp v216, v156, v96 row_shr:1 row_mask:0xf bank_mask:0xf
	v_fmac_f32_dpp v218, v148, v96 row_shr:1 row_mask:0xf bank_mask:0xf
	v_fmac_f32_dpp v220, v158, v98 row_shr:1 row_mask:0xf bank_mask:0xf
	v_fmac_f32_dpp v222, v150, v98 row_shr:1 row_mask:0xf bank_mask:0xf
	v_fmac_f32_dpp v224, v152, v112 row_shr:1 row_mask:0xf bank_mask:0xf
	v_fmac_f32_dpp v226, v144, v112 row_shr:1 row_mask:0xf bank_mask:0xf
	v_fmac_f32_dpp v228, v154, v114 row_shr:1 row_mask:0xf bank_mask:0xf
	v_fmac_f32_dpp v194, v146, v114 row_shr:1 row_mask:0xf bank_mask:0xf
	v_fmac_f32_dpp v216, v156, v104 row_shl:1 row_mask:0xf bank_mask:0xf
	v_fmac_f32_dpp v218, v148, v104 row_shl:1 row_mask:0xf bank_mask:0xf
	v_fmac_f32_dpp v220, v158, v106 row_shl:1 row_mask:0xf bank_mask:0xf
	v_fmac_f32_dpp v222, v150, v106 row_shl:1 row_mask:0xf bank_mask:0xf
	v_fmac_f32_dpp v224, v152, v120 row_shl:1 row_mask:0xf bank_mask:0xf
	v_fmac_f32_dpp v226, v144, v120 row_shl:1 row_mask:0xf bank_mask:0xf
	v_fmac_f32_dpp v228, v154, v122 row_shl:1 row_mask:0xf bank_mask:0xf
	v_fmac_f32_dpp v194, v146, v122 row_shl:1 row_mask:0xf bank_mask:0xf
	v_fmac_f32_dpp v216, v148, v204 row_ror:15 row_mask:0xf bank_mask:0xf
	v_fmac_f32_dpp v218, v156, v200 row_ror:1 row_mask:0xf bank_mask:0xf
	v_fmac_f32_dpp v220, v150, v206 row_ror:15 row_mask:0xf bank_mask:0xf
	v_fmac_f32_dpp v222, v158, v202 row_ror:1 row_mask:0xf bank_mask:0xf
	v_fmac_f32_dpp v224, v144, v212 row_ror:15 row_mask:0xf bank_mask:0xf
	v_fmac_f32_dpp v226, v152, v208 row_ror:1 row_mask:0xf bank_mask:0xf
	v_fmac_f32_dpp v228, v146, v214 row_ror:15 row_mask:0xf bank_mask:0xf
	v_fmac_f32_dpp v194, v154, v210 row_ror:1 row_mask:0xf bank_mask:0xf
	v_fmac_f32_dpp v217, v157, v97 row_shr:1 row_mask:0xf bank_mask:0xf
	v_fmac_f32_dpp v218, v140, v204 row_ror:15 row_mask:0xf bank_mask:0xf
	v_fmac_f32_dpp v221, v159, v99 row_shr:1 row_mask:0xf bank_mask:0xf
	v_fmac_f32_dpp v222, v142, v206 row_ror:15 row_mask:0xf bank_mask:0xf
	v_fmac_f32_dpp v225, v153, v113 row_shr:1 row_mask:0xf bank_mask:0xf
	v_fmac_f32_dpp v226, v136, v212 row_ror:15 row_mask:0xf bank_mask:0xf
	v_fmac_f32_dpp v229, v155, v115 row_shr:1 row_mask:0xf bank_mask:0xf
	v_fmac_f32_dpp v194, v138, v214 row_ror:15 row_mask:0xf bank_mask:0xf
	v_fmac_f32_dpp v217, v157, v105 row_shl:1 row_mask:0xf bank_mask:0xf
	v_fmac_f32_dpp v219, v149, v97 row_shr:1 row_mask:0xf bank_mask:0xf
	v_fmac_f32_dpp v221, v159, v107 row_shl:1 row_mask:0xf bank_mask:0xf
	v_fmac_f32_dpp v223, v151, v99 row_shr:1 row_mask:0xf bank_mask:0xf
	v_fmac_f32_dpp v225, v153, v121 row_shl:1 row_mask:0xf bank_mask:0xf
	v_fmac_f32_dpp v227, v145, v113 row_shr:1 row_mask:0xf bank_mask:0xf
	v_fmac_f32_dpp v229, v155, v123 row_shl:1 row_mask:0xf bank_mask:0xf
	v_fmac_f32_dpp v195, v147, v115 row_shr:1 row_mask:0xf bank_mask:0xf
	v_fmac_f32_dpp v217, v149, v205 row_ror:15 row_mask:0xf bank_mask:0xf
	v_fmac_f32_dpp v219, v149, v105 row_shl:1 row_mask:0xf bank_mask:0xf
	v_fmac_f32_dpp v221, v151, v207 row_ror:15 row_mask:0xf bank_mask:0xf
;     DI void operator()(const f32x4 (&acc)[2][2][4][2], const Unit& u, int wr, int wc, int fr_, int fq_) const {
;     ...
;                 for (int m = 0; m < 4; ++m) { f32x4 zv, zg;
;                     CONV_ONE(acc, ai, 0, n, m, zv, vp, vm, vn); CONV_ONE(acc, ai, 1, n, m, zg, gp, gm, gn);
;                     zv = zv + vb; zg = zg + gb;
;                     float ov[4];
; #pragma unroll
;                     for (int e = 0; e < 4; ++e) { const float x = zg[e]; const float uu = 1.5957691216f * (x + 0.044715f * x * x * x);
;                         ov[e] = zv[e] * x * __builtin_amdgcn_rcpf(1.f + __expf(-uu)); }
	v_fmac_f32_dpp v223, v151, v107 row_shl:1 row_mask:0xf bank_mask:0xf
	v_fmac_f32_dpp v225, v145, v213 row_ror:15 row_mask:0xf bank_mask:0xf
	v_fmac_f32_dpp v227, v145, v121 row_shl:1 row_mask:0xf bank_mask:0xf
	v_fmac_f32_dpp v229, v147, v215 row_ror:15 row_mask:0xf bank_mask:0xf
	v_fmac_f32_dpp v195, v147, v123 row_shl:1 row_mask:0xf bank_mask:0xf
	v_fmac_f32_dpp v219, v157, v201 row_ror:1 row_mask:0xf bank_mask:0xf
	v_fmac_f32_dpp v223, v159, v203 row_ror:1 row_mask:0xf bank_mask:0xf
	v_fmac_f32_dpp v227, v153, v209 row_ror:1 row_mask:0xf bank_mask:0xf
	v_fmac_f32_dpp v195, v155, v211 row_ror:1 row_mask:0xf bank_mask:0xf
	v_fmac_f32_dpp v219, v141, v205 row_ror:15 row_mask:0xf bank_mask:0xf
	v_fmac_f32_dpp v223, v143, v207 row_ror:15 row_mask:0xf bank_mask:0xf
	v_fmac_f32_dpp v227, v137, v213 row_ror:15 row_mask:0xf bank_mask:0xf
	v_fmac_f32_dpp v195, v139, v215 row_ror:15 row_mask:0xf bank_mask:0xf
	v_pk_fma_f32 v[156:157], v[140:141], v[100:101], v[108:109]
	v_pk_fma_f32 v[158:159], v[142:143], v[102:103], v[110:111]
	v_pk_fma_f32 v[152:153], v[136:137], v[116:117], v[124:125]
	v_pk_fma_f32 v[154:155], v[138:139], v[118:119], v[126:127]
	v_fmac_f32_dpp v156, v140, v96 row_shr:1 row_mask:0xf bank_mask:0xf
	v_fmac_f32_dpp v158, v142, v98 row_shr:1 row_mask:0xf bank_mask:0xf
	v_fmac_f32_dpp v152, v136, v112 row_shr:1 row_mask:0xf bank_mask:0xf
	v_fmac_f32_dpp v154, v138, v114 row_shr:1 row_mask:0xf bank_mask:0xf
	v_fmac_f32_dpp v156, v140, v104 row_shl:1 row_mask:0xf bank_mask:0xf
	v_fmac_f32_dpp v158, v142, v106 row_shl:1 row_mask:0xf bank_mask:0xf
	v_fmac_f32_dpp v152, v136, v120 row_shl:1 row_mask:0xf bank_mask:0xf
	v_fmac_f32_dpp v154, v138, v122 row_shl:1 row_mask:0xf bank_mask:0xf
	v_fmac_f32_dpp v156, v148, v200 row_ror:1 row_mask:0xf bank_mask:0xf
	v_fmac_f32_dpp v158, v150, v202 row_ror:1 row_mask:0xf bank_mask:0xf
	v_fmac_f32_dpp v152, v144, v208 row_ror:1 row_mask:0xf bank_mask:0xf
	v_fmac_f32_dpp v154, v146, v210 row_ror:1 row_mask:0xf bank_mask:0xf
	v_fmac_f32_dpp v156, v132, v204 row_ror:15 row_mask:0xf bank_mask:0xf
	v_fmac_f32_dpp v158, v134, v206 row_ror:15 row_mask:0xf bank_mask:0xf
	v_fmac_f32_dpp v152, v128, v212 row_ror:15 row_mask:0xf bank_mask:0xf
	v_fmac_f32_dpp v154, v130, v214 row_ror:15 row_mask:0xf bank_mask:0xf
	v_fmac_f32_dpp v157, v141, v97 row_shr:1 row_mask:0xf bank_mask:0xf
	v_fmac_f32_dpp v159, v143, v99 row_shr:1 row_mask:0xf bank_mask:0xf
	v_fmac_f32_dpp v153, v137, v113 row_shr:1 row_mask:0xf bank_mask:0xf
	v_fmac_f32_dpp v155, v139, v115 row_shr:1 row_mask:0xf bank_mask:0xf
	v_fmac_f32_dpp v157, v141, v105 row_shl:1 row_mask:0xf bank_mask:0xf
	v_fmac_f32_dpp v159, v143, v107 row_shl:1 row_mask:0xf bank_mask:0xf
	v_fmac_f32_dpp v153, v137, v121 row_shl:1 row_mask:0xf bank_mask:0xf
	v_fmac_f32_dpp v155, v139, v123 row_shl:1 row_mask:0xf bank_mask:0xf
	v_fmac_f32_dpp v157, v149, v201 row_ror:1 row_mask:0xf bank_mask:0xf
	v_fmac_f32_dpp v159, v151, v203 row_ror:1 row_mask:0xf bank_mask:0xf
	v_fmac_f32_dpp v153, v145, v209 row_ror:1 row_mask:0xf bank_mask:0xf
	v_fmac_f32_dpp v155, v147, v211 row_ror:1 row_mask:0xf bank_mask:0xf
	v_fmac_f32_dpp v157, v133, v205 row_ror:15 row_mask:0xf bank_mask:0xf
	v_fmac_f32_dpp v159, v135, v207 row_ror:15 row_mask:0xf bank_mask:0xf
	v_fmac_f32_dpp v153, v129, v213 row_ror:15 row_mask:0xf bank_mask:0xf
	v_fmac_f32_dpp v155, v131, v215 row_ror:15 row_mask:0xf bank_mask:0xf
	v_pk_fma_f32 v[148:149], v[132:133], v[100:101], v[108:109]
	v_pk_fma_f32 v[150:151], v[134:135], v[102:103], v[110:111]
	v_pk_fma_f32 v[144:145], v[128:129], v[116:117], v[124:125]
	v_pk_fma_f32 v[146:147], v[130:131], v[118:119], v[126:127]
	v_fmac_f32_dpp v148, v132, v96 row_shr:1 row_mask:0xf bank_mask:0xf
	v_fmac_f32_dpp v150, v134, v98 row_shr:1 row_mask:0xf bank_mask:0xf
	v_fmac_f32_dpp v144, v128, v112 row_shr:1 row_mask:0xf bank_mask:0xf
	v_fmac_f32_dpp v146, v130, v114 row_shr:1 row_mask:0xf bank_mask:0xf
	v_fmac_f32_dpp v148, v132, v104 row_shl:1 row_mask:0xf bank_mask:0xf
	v_fmac_f32_dpp v150, v134, v106 row_shl:1 row_mask:0xf bank_mask:0xf
	v_fmac_f32_dpp v144, v128, v120 row_shl:1 row_mask:0xf bank_mask:0xf
	v_fmac_f32_dpp v146, v130, v122 row_shl:1 row_mask:0xf bank_mask:0xf
	v_fmac_f32_dpp v148, v140, v200 row_ror:1 row_mask:0xf bank_mask:0xf
	v_fmac_f32_dpp v150, v142, v202 row_ror:1 row_mask:0xf bank_mask:0xf
	v_fmac_f32_dpp v144, v136, v208 row_ror:1 row_mask:0xf bank_mask:0xf
	v_fmac_f32_dpp v146, v138, v210 row_ror:1 row_mask:0xf bank_mask:0xf
	v_fmac_f32_dpp v149, v133, v97 row_shr:1 row_mask:0xf bank_mask:0xf
	v_fmac_f32_dpp v151, v135, v99 row_shr:1 row_mask:0xf bank_mask:0xf
	v_fmac_f32_dpp v145, v129, v113 row_shr:1 row_mask:0xf bank_mask:0xf
	v_fmac_f32_dpp v147, v131, v115 row_shr:1 row_mask:0xf bank_mask:0xf
	v_fmac_f32_dpp v149, v133, v105 row_shl:1 row_mask:0xf bank_mask:0xf
	v_fmac_f32_dpp v151, v135, v107 row_shl:1 row_mask:0xf bank_mask:0xf
	v_fmac_f32_dpp v145, v129, v121 row_shl:1 row_mask:0xf bank_mask:0xf
	v_fmac_f32_dpp v147, v131, v123 row_shl:1 row_mask:0xf bank_mask:0xf
	v_fmac_f32_dpp v149, v141, v201 row_ror:1 row_mask:0xf bank_mask:0xf
	v_fmac_f32_dpp v151, v143, v203 row_ror:1 row_mask:0xf bank_mask:0xf
	v_fmac_f32_dpp v145, v137, v209 row_ror:1 row_mask:0xf bank_mask:0xf
	v_fmac_f32_dpp v147, v139, v211 row_ror:1 row_mask:0xf bank_mask:0xf
	v_pk_mul_f32 v[172:173], v[224:225], s[40:41] op_sel_hi:[1,0]
	v_pk_mul_f32 v[174:175], v[228:229], s[40:41] op_sel_hi:[1,0]
	v_pk_mul_f32 v[172:173], v[224:225], v[172:173]
	v_pk_mul_f32 v[174:175], v[228:229], v[174:175]
	v_pk_fma_f32 v[172:173], v[224:225], v[172:173], v[224:225]
	v_pk_fma_f32 v[174:175], v[228:229], v[174:175], v[228:229]
; DI unsigned cvtpk(float lo, float hi) { unsigned r; asm volatile("v_cvt_pk_bf16_f32 %0, %1, %2" : "=v"(r) : "v"(lo), "v"(hi)); return r; }
;     DI void operator()(const f32x4 (&acc)[2][2][4][2], const Unit& u, int wr, int wc, int fr_, int fq_) const {
;     ...
;             for (int ai = 0; ai < 2; ++ai) {
;                 const int tok0 = u.pm * 248 + (2 * ai + wr) * 62 - 1;
; #pragma unroll
;                 for (int m = 0; m < 4; ++m) { f32x4 zv, zg;
;                     CONV_ONE(acc, ai, 0, n, m, zv, vp, vm, vn); CONV_ONE(acc, ai, 1, n, m, zg, gp, gm, gn);
;                     zv = zv + vb; zg = zg + gb;
;                     float ov[4];
; #pragma unroll
;                     for (int e = 0; e < 4; ++e) { const float x = zg[e]; const float uu = 1.5957691216f * (x + 0.044715f * x * x * x);
;                         ov[e] = zv[e] * x * __builtin_amdgcn_rcpf(1.f + __expf(-uu)); }
;                     if (ROW_VALID(m)) { const int t = tok0 + 16 * m + fr; u32x2 w; w.x = cvtpk(ov[0], ov[1]); w.y = cvtpk(ov[2], ov[3]);
;                         *(u32x2*)(ACT + (size_t)t * FF + cv0 + 4 * n) = w; }
;                     __builtin_amdgcn_sched_barrier(0); }
	v_pk_mul_f32 v[172:173], v[172:173], s[42:43] op_sel_hi:[1,0]
	v_pk_mul_f32 v[174:175], v[174:175], s[42:43] op_sel_hi:[1,0]
	v_pk_mul_f32 v[176:177], v[216:217], v[224:225]
	v_pk_mul_f32 v[178:179], v[220:221], v[228:229]
	v_exp_f32_e32 v172, v172
	v_exp_f32_e32 v173, v173
	v_exp_f32_e32 v174, v174
	v_exp_f32_e32 v175, v175
	v_pk_add_f32 v[172:173], v[172:173], s[44:45] op_sel_hi:[1,0]
	v_pk_add_f32 v[174:175], v[174:175], s[44:45] op_sel_hi:[1,0]
	v_rcp_f32_e32 v172, v172
	v_rcp_f32_e32 v173, v173
	v_rcp_f32_e32 v174, v174
	v_rcp_f32_e32 v175, v175
	s_mov_b32 s26, 0x0
	v_lshl_add_u64 v[170:171], v[186:187], 0, s[26:27]
	v_pk_mul_f32 v[176:177], v[176:177], v[172:173]
	v_pk_mul_f32 v[178:179], v[178:179], v[174:175]
	s_and_b64 exec, s[28:29], s[14:15]
	v_cvt_pk_bf16_f32 v176, v176, v177
	v_cvt_pk_bf16_f32 v177, v178, v179
	global_store_dwordx2 v[170:171], v[176:177], off offset:0
	s_mov_b64 exec, s[28:29]
	v_pk_mul_f32 v[172:173], v[226:227], s[40:41] op_sel_hi:[1,0]
	v_pk_mul_f32 v[174:175], v[194:195], s[40:41] op_sel_hi:[1,0]
	v_pk_mul_f32 v[172:173], v[226:227], v[172:173]
	v_pk_mul_f32 v[174:175], v[194:195], v[174:175]
	v_pk_fma_f32 v[172:173], v[226:227], v[172:173], v[226:227]
	v_pk_fma_f32 v[174:175], v[194:195], v[174:175], v[194:195]
	v_pk_mul_f32 v[172:173], v[172:173], s[42:43] op_sel_hi:[1,0]
	v_pk_mul_f32 v[174:175], v[174:175], s[42:43] op_sel_hi:[1,0]
	v_pk_mul_f32 v[176:177], v[218:219], v[226:227]
	v_pk_mul_f32 v[178:179], v[222:223], v[194:195]
	v_exp_f32_e32 v172, v172
	v_exp_f32_e32 v173, v173
	v_exp_f32_e32 v174, v174
	v_exp_f32_e32 v175, v175
	v_pk_add_f32 v[172:173], v[172:173], s[44:45] op_sel_hi:[1,0]
	v_pk_add_f32 v[174:175], v[174:175], s[44:45] op_sel_hi:[1,0]
	v_rcp_f32_e32 v172, v172
	v_rcp_f32_e32 v173, v173
	v_rcp_f32_e32 v174, v174
	v_rcp_f32_e32 v175, v175
	s_mov_b32 s26, 0x16000
	v_lshl_add_u64 v[170:171], v[186:187], 0, s[26:27]
	v_pk_mul_f32 v[176:177], v[176:177], v[172:173]
	v_pk_mul_f32 v[178:179], v[178:179], v[174:175]
	v_cvt_pk_bf16_f32 v176, v176, v177
	v_cvt_pk_bf16_f32 v177, v178, v179
	global_store_dwordx2 v[170:171], v[176:177], off offset:0
	v_pk_mul_f32 v[172:173], v[152:153], s[40:41] op_sel_hi:[1,0]
	v_pk_mul_f32 v[174:175], v[154:155], s[40:41] op_sel_hi:[1,0]
	v_pk_mul_f32 v[172:173], v[152:153], v[172:173]
	v_pk_mul_f32 v[174:175], v[154:155], v[174:175]
	v_pk_fma_f32 v[172:173], v[152:153], v[172:173], v[152:153]
	v_pk_fma_f32 v[174:175], v[154:155], v[174:175], v[154:155]
	v_pk_mul_f32 v[172:173], v[172:173], s[42:43] op_sel_hi:[1,0]
	v_pk_mul_f32 v[174:175], v[174:175], s[42:43] op_sel_hi:[1,0]
	v_pk_mul_f32 v[176:177], v[156:157], v[152:153]
	v_pk_mul_f32 v[178:179], v[158:159], v[154:155]
	v_exp_f32_e32 v172, v172
	v_exp_f32_e32 v173, v173
	v_exp_f32_e32 v174, v174
	v_exp_f32_e32 v175, v175
	v_pk_add_f32 v[172:173], v[172:173], s[44:45] op_sel_hi:[1,0]
	v_pk_add_f32 v[174:175], v[174:175], s[44:45] op_sel_hi:[1,0]
	v_rcp_f32_e32 v172, v172
	v_rcp_f32_e32 v173, v173
	v_rcp_f32_e32 v174, v174
	v_rcp_f32_e32 v175, v175
	s_mov_b32 s26, 0x2c000
	v_lshl_add_u64 v[170:171], v[186:187], 0, s[26:27]
	v_pk_mul_f32 v[176:177], v[176:177], v[172:173]
	v_pk_mul_f32 v[178:179], v[178:179], v[174:175]
	v_cvt_pk_bf16_f32 v176, v176, v177
	v_cvt_pk_bf16_f32 v177, v178, v179
	global_store_dwordx2 v[170:171], v[176:177], off offset:0
	v_pk_mul_f32 v[172:173], v[144:145], s[40:41] op_sel_hi:[1,0]
	v_pk_mul_f32 v[174:175], v[146:147], s[40:41] op_sel_hi:[1,0]
	v_pk_mul_f32 v[172:173], v[144:145], v[172:173]
	v_pk_mul_f32 v[174:175], v[146:147], v[174:175]
	v_pk_fma_f32 v[172:173], v[144:145], v[172:173], v[144:145]
	v_pk_fma_f32 v[174:175], v[146:147], v[174:175], v[146:147]
	v_pk_mul_f32 v[172:173], v[172:173], s[42:43] op_sel_hi:[1,0]
	v_pk_mul_f32 v[174:175], v[174:175], s[42:43] op_sel_hi:[1,0]
	v_pk_mul_f32 v[176:177], v[148:149], v[144:145]
	v_pk_mul_f32 v[178:179], v[150:151], v[146:147]
	v_exp_f32_e32 v172, v172
	v_exp_f32_e32 v173, v173
	v_exp_f32_e32 v174, v174
	v_exp_f32_e32 v175, v175
	v_pk_add_f32 v[172:173], v[172:173], s[44:45] op_sel_hi:[1,0]
	v_pk_add_f32 v[174:175], v[174:175], s[44:45] op_sel_hi:[1,0]
	v_rcp_f32_e32 v172, v172
	v_rcp_f32_e32 v173, v173
	v_rcp_f32_e32 v174, v174
	v_rcp_f32_e32 v175, v175
	s_mov_b32 s26, 0x42000
	v_lshl_add_u64 v[170:171], v[186:187], 0, s[26:27]
	v_pk_mul_f32 v[176:177], v[176:177], v[172:173]
	v_pk_mul_f32 v[178:179], v[178:179], v[174:175]
	s_and_b64 exec, s[28:29], s[24:25]
	v_cvt_pk_bf16_f32 v176, v176, v177
	v_cvt_pk_bf16_f32 v177, v178, v179
	global_store_dwordx2 v[170:171], v[176:177], off offset:0
	s_mov_b64 exec, s[28:29]
	v_pk_fma_f32 v[216:217], v[92:93], v[100:101], v[108:109]
	v_pk_fma_f32 v[218:219], v[84:85], v[100:101], v[108:109]
	v_pk_fma_f32 v[220:221], v[94:95], v[102:103], v[110:111]
	v_pk_fma_f32 v[222:223], v[86:87], v[102:103], v[110:111]
	v_pk_fma_f32 v[224:225], v[88:89], v[116:117], v[124:125]
	v_pk_fma_f32 v[226:227], v[80:81], v[116:117], v[124:125]
	v_pk_fma_f32 v[228:229], v[90:91], v[118:119], v[126:127]
	v_pk_fma_f32 v[194:195], v[82:83], v[118:119], v[126:127]
	v_fmac_f32_dpp v216, v92, v96 row_shr:1 row_mask:0xf bank_mask:0xf
	v_fmac_f32_dpp v218, v84, v96 row_shr:1 row_mask:0xf bank_mask:0xf
	v_fmac_f32_dpp v220, v94, v98 row_shr:1 row_mask:0xf bank_mask:0xf
	v_fmac_f32_dpp v222, v86, v98 row_shr:1 row_mask:0xf bank_mask:0xf
	v_fmac_f32_dpp v224, v88, v112 row_shr:1 row_mask:0xf bank_mask:0xf
	v_fmac_f32_dpp v226, v80, v112 row_shr:1 row_mask:0xf bank_mask:0xf
	v_fmac_f32_dpp v228, v90, v114 row_shr:1 row_mask:0xf bank_mask:0xf
	v_fmac_f32_dpp v194, v82, v114 row_shr:1 row_mask:0xf bank_mask:0xf
;     DI void operator()(const f32x4 (&acc)[2][2][4][2], const Unit& u, int wr, int wc, int fr_, int fq_) const {
;     ...
;             for (int ai = 0; ai < 2; ++ai) {
;                 const int tok0 = u.pm * 248 + (2 * ai + wr) * 62 - 1;
; #pragma unroll
;                 for (int m = 0; m < 4; ++m) { f32x4 zv, zg;
;                     CONV_ONE(acc, ai, 0, n, m, zv, vp, vm, vn); CONV_ONE(acc, ai, 1, n, m, zg, gp, gm, gn);
;                     zv = zv + vb; zg = zg + gb;
;                     float ov[4];
; #pragma unroll
;                     for (int e = 0; e < 4; ++e) { const float x = zg[e]; const float uu = 1.5957691216f * (x + 0.044715f * x * x * x);
;                         ov[e] = zv[e] * x * __builtin_amdgcn_rcpf(1.f + __expf(-uu)); }
	v_fmac_f32_dpp v216, v92, v104 row_shl:1 row_mask:0xf bank_mask:0xf
	v_fmac_f32_dpp v218, v84, v104 row_shl:1 row_mask:0xf bank_mask:0xf
	v_fmac_f32_dpp v220, v94, v106 row_shl:1 row_mask:0xf bank_mask:0xf
	v_fmac_f32_dpp v222, v86, v106 row_shl:1 row_mask:0xf bank_mask:0xf
	v_fmac_f32_dpp v224, v88, v120 row_shl:1 row_mask:0xf bank_mask:0xf
	v_fmac_f32_dpp v226, v80, v120 row_shl:1 row_mask:0xf bank_mask:0xf
	v_fmac_f32_dpp v228, v90, v122 row_shl:1 row_mask:0xf bank_mask:0xf
	v_fmac_f32_dpp v194, v82, v122 row_shl:1 row_mask:0xf bank_mask:0xf
	v_fmac_f32_dpp v216, v84, v204 row_ror:15 row_mask:0xf bank_mask:0xf
	v_fmac_f32_dpp v218, v92, v200 row_ror:1 row_mask:0xf bank_mask:0xf
	v_fmac_f32_dpp v220, v86, v206 row_ror:15 row_mask:0xf bank_mask:0xf
	v_fmac_f32_dpp v222, v94, v202 row_ror:1 row_mask:0xf bank_mask:0xf
	v_fmac_f32_dpp v224, v80, v212 row_ror:15 row_mask:0xf bank_mask:0xf
	v_fmac_f32_dpp v226, v88, v208 row_ror:1 row_mask:0xf bank_mask:0xf
	v_fmac_f32_dpp v228, v82, v214 row_ror:15 row_mask:0xf bank_mask:0xf
	v_fmac_f32_dpp v194, v90, v210 row_ror:1 row_mask:0xf bank_mask:0xf
	v_fmac_f32_dpp v217, v93, v97 row_shr:1 row_mask:0xf bank_mask:0xf
	v_fmac_f32_dpp v218, v76, v204 row_ror:15 row_mask:0xf bank_mask:0xf
	v_fmac_f32_dpp v221, v95, v99 row_shr:1 row_mask:0xf bank_mask:0xf
	v_fmac_f32_dpp v222, v78, v206 row_ror:15 row_mask:0xf bank_mask:0xf
	v_fmac_f32_dpp v225, v89, v113 row_shr:1 row_mask:0xf bank_mask:0xf
	v_fmac_f32_dpp v226, v72, v212 row_ror:15 row_mask:0xf bank_mask:0xf
	v_fmac_f32_dpp v229, v91, v115 row_shr:1 row_mask:0xf bank_mask:0xf
	v_fmac_f32_dpp v194, v74, v214 row_ror:15 row_mask:0xf bank_mask:0xf
	v_fmac_f32_dpp v217, v93, v105 row_shl:1 row_mask:0xf bank_mask:0xf
	v_fmac_f32_dpp v219, v85, v97 row_shr:1 row_mask:0xf bank_mask:0xf
	v_fmac_f32_dpp v221, v95, v107 row_shl:1 row_mask:0xf bank_mask:0xf
	v_fmac_f32_dpp v223, v87, v99 row_shr:1 row_mask:0xf bank_mask:0xf
	v_fmac_f32_dpp v225, v89, v121 row_shl:1 row_mask:0xf bank_mask:0xf
	v_fmac_f32_dpp v227, v81, v113 row_shr:1 row_mask:0xf bank_mask:0xf
	v_fmac_f32_dpp v229, v91, v123 row_shl:1 row_mask:0xf bank_mask:0xf
	v_fmac_f32_dpp v195, v83, v115 row_shr:1 row_mask:0xf bank_mask:0xf
	v_fmac_f32_dpp v217, v85, v205 row_ror:15 row_mask:0xf bank_mask:0xf
	v_fmac_f32_dpp v219, v85, v105 row_shl:1 row_mask:0xf bank_mask:0xf
	v_fmac_f32_dpp v221, v87, v207 row_ror:15 row_mask:0xf bank_mask:0xf
	v_fmac_f32_dpp v223, v87, v107 row_shl:1 row_mask:0xf bank_mask:0xf
	v_fmac_f32_dpp v225, v81, v213 row_ror:15 row_mask:0xf bank_mask:0xf
	v_fmac_f32_dpp v227, v81, v121 row_shl:1 row_mask:0xf bank_mask:0xf
	v_fmac_f32_dpp v229, v83, v215 row_ror:15 row_mask:0xf bank_mask:0xf
	v_fmac_f32_dpp v195, v83, v123 row_shl:1 row_mask:0xf bank_mask:0xf
	v_fmac_f32_dpp v219, v93, v201 row_ror:1 row_mask:0xf bank_mask:0xf
	v_fmac_f32_dpp v223, v95, v203 row_ror:1 row_mask:0xf bank_mask:0xf
	v_fmac_f32_dpp v227, v89, v209 row_ror:1 row_mask:0xf bank_mask:0xf
	v_fmac_f32_dpp v195, v91, v211 row_ror:1 row_mask:0xf bank_mask:0xf
	v_fmac_f32_dpp v219, v77, v205 row_ror:15 row_mask:0xf bank_mask:0xf
	v_fmac_f32_dpp v223, v79, v207 row_ror:15 row_mask:0xf bank_mask:0xf
	v_fmac_f32_dpp v227, v73, v213 row_ror:15 row_mask:0xf bank_mask:0xf
	v_fmac_f32_dpp v195, v75, v215 row_ror:15 row_mask:0xf bank_mask:0xf
	v_pk_fma_f32 v[92:93], v[76:77], v[100:101], v[108:109]
	v_pk_fma_f32 v[94:95], v[78:79], v[102:103], v[110:111]
	v_pk_fma_f32 v[88:89], v[72:73], v[116:117], v[124:125]
	v_pk_fma_f32 v[90:91], v[74:75], v[118:119], v[126:127]
	v_fmac_f32_dpp v92, v76, v96 row_shr:1 row_mask:0xf bank_mask:0xf
	v_fmac_f32_dpp v94, v78, v98 row_shr:1 row_mask:0xf bank_mask:0xf
	v_fmac_f32_dpp v88, v72, v112 row_shr:1 row_mask:0xf bank_mask:0xf
	v_fmac_f32_dpp v90, v74, v114 row_shr:1 row_mask:0xf bank_mask:0xf
	v_fmac_f32_dpp v92, v76, v104 row_shl:1 row_mask:0xf bank_mask:0xf
	v_fmac_f32_dpp v94, v78, v106 row_shl:1 row_mask:0xf bank_mask:0xf
	v_fmac_f32_dpp v88, v72, v120 row_shl:1 row_mask:0xf bank_mask:0xf
	v_fmac_f32_dpp v90, v74, v122 row_shl:1 row_mask:0xf bank_mask:0xf
	v_fmac_f32_dpp v92, v84, v200 row_ror:1 row_mask:0xf bank_mask:0xf
	v_fmac_f32_dpp v94, v86, v202 row_ror:1 row_mask:0xf bank_mask:0xf
	v_fmac_f32_dpp v88, v80, v208 row_ror:1 row_mask:0xf bank_mask:0xf
	v_fmac_f32_dpp v90, v82, v210 row_ror:1 row_mask:0xf bank_mask:0xf
	v_fmac_f32_dpp v92, v68, v204 row_ror:15 row_mask:0xf bank_mask:0xf
	v_fmac_f32_dpp v94, v70, v206 row_ror:15 row_mask:0xf bank_mask:0xf
	v_fmac_f32_dpp v88, v64, v212 row_ror:15 row_mask:0xf bank_mask:0xf
	v_fmac_f32_dpp v90, v66, v214 row_ror:15 row_mask:0xf bank_mask:0xf
	v_fmac_f32_dpp v93, v77, v97 row_shr:1 row_mask:0xf bank_mask:0xf
	v_fmac_f32_dpp v95, v79, v99 row_shr:1 row_mask:0xf bank_mask:0xf
	v_fmac_f32_dpp v89, v73, v113 row_shr:1 row_mask:0xf bank_mask:0xf
	v_fmac_f32_dpp v91, v75, v115 row_shr:1 row_mask:0xf bank_mask:0xf
	v_fmac_f32_dpp v93, v77, v105 row_shl:1 row_mask:0xf bank_mask:0xf
	v_fmac_f32_dpp v95, v79, v107 row_shl:1 row_mask:0xf bank_mask:0xf
	v_fmac_f32_dpp v89, v73, v121 row_shl:1 row_mask:0xf bank_mask:0xf
	v_fmac_f32_dpp v91, v75, v123 row_shl:1 row_mask:0xf bank_mask:0xf
	v_fmac_f32_dpp v93, v85, v201 row_ror:1 row_mask:0xf bank_mask:0xf
	v_fmac_f32_dpp v95, v87, v203 row_ror:1 row_mask:0xf bank_mask:0xf
	v_fmac_f32_dpp v89, v81, v209 row_ror:1 row_mask:0xf bank_mask:0xf
	v_fmac_f32_dpp v91, v83, v211 row_ror:1 row_mask:0xf bank_mask:0xf
	v_fmac_f32_dpp v93, v69, v205 row_ror:15 row_mask:0xf bank_mask:0xf
	v_fmac_f32_dpp v95, v71, v207 row_ror:15 row_mask:0xf bank_mask:0xf
	v_fmac_f32_dpp v89, v65, v213 row_ror:15 row_mask:0xf bank_mask:0xf
; DI unsigned cvtpk(float lo, float hi) { unsigned r; asm volatile("v_cvt_pk_bf16_f32 %0, %1, %2" : "=v"(r) : "v"(lo), "v"(hi)); return r; }
;     DI void operator()(const f32x4 (&acc)[2][2][4][2], const Unit& u, int wr, int wc, int fr_, int fq_) const {
;     ...
;                 for (int m = 0; m < 4; ++m) { f32x4 zv, zg;
;                     CONV_ONE(acc, ai, 0, n, m, zv, vp, vm, vn); CONV_ONE(acc, ai, 1, n, m, zg, gp, gm, gn);
;                     zv = zv + vb; zg = zg + gb;
;                     float ov[4];
; #pragma unroll
;                     for (int e = 0; e < 4; ++e) { const float x = zg[e]; const float uu = 1.5957691216f * (x + 0.044715f * x * x * x);
;                         ov[e] = zv[e] * x * __builtin_amdgcn_rcpf(1.f + __expf(-uu)); }
;                     if (ROW_VALID(m)) { const int t = tok0 + 16 * m + fr; u32x2 w; w.x = cvtpk(ov[0], ov[1]); w.y = cvtpk(ov[2], ov[3]);
;                         *(u32x2*)(ACT + (size_t)t * FF + cv0 + 4 * n) = w; }
;                     __builtin_amdgcn_sched_barrier(0); }
	v_fmac_f32_dpp v91, v67, v215 row_ror:15 row_mask:0xf bank_mask:0xf
	v_pk_fma_f32 v[84:85], v[68:69], v[100:101], v[108:109]
	v_pk_fma_f32 v[86:87], v[70:71], v[102:103], v[110:111]
	v_pk_fma_f32 v[80:81], v[64:65], v[116:117], v[124:125]
	v_pk_fma_f32 v[82:83], v[66:67], v[118:119], v[126:127]
	v_fmac_f32_dpp v84, v68, v96 row_shr:1 row_mask:0xf bank_mask:0xf
	v_fmac_f32_dpp v86, v70, v98 row_shr:1 row_mask:0xf bank_mask:0xf
	v_fmac_f32_dpp v80, v64, v112 row_shr:1 row_mask:0xf bank_mask:0xf
	v_fmac_f32_dpp v82, v66, v114 row_shr:1 row_mask:0xf bank_mask:0xf
	v_fmac_f32_dpp v84, v68, v104 row_shl:1 row_mask:0xf bank_mask:0xf
	v_fmac_f32_dpp v86, v70, v106 row_shl:1 row_mask:0xf bank_mask:0xf
	v_fmac_f32_dpp v80, v64, v120 row_shl:1 row_mask:0xf bank_mask:0xf
	v_fmac_f32_dpp v82, v66, v122 row_shl:1 row_mask:0xf bank_mask:0xf
	v_fmac_f32_dpp v84, v76, v200 row_ror:1 row_mask:0xf bank_mask:0xf
	v_fmac_f32_dpp v86, v78, v202 row_ror:1 row_mask:0xf bank_mask:0xf
	v_fmac_f32_dpp v80, v72, v208 row_ror:1 row_mask:0xf bank_mask:0xf
	v_fmac_f32_dpp v82, v74, v210 row_ror:1 row_mask:0xf bank_mask:0xf
	v_fmac_f32_dpp v85, v69, v97 row_shr:1 row_mask:0xf bank_mask:0xf
	v_fmac_f32_dpp v87, v71, v99 row_shr:1 row_mask:0xf bank_mask:0xf
	v_fmac_f32_dpp v81, v65, v113 row_shr:1 row_mask:0xf bank_mask:0xf
	v_fmac_f32_dpp v83, v67, v115 row_shr:1 row_mask:0xf bank_mask:0xf
	v_fmac_f32_dpp v85, v69, v105 row_shl:1 row_mask:0xf bank_mask:0xf
	v_fmac_f32_dpp v87, v71, v107 row_shl:1 row_mask:0xf bank_mask:0xf
	v_fmac_f32_dpp v81, v65, v121 row_shl:1 row_mask:0xf bank_mask:0xf
	v_fmac_f32_dpp v83, v67, v123 row_shl:1 row_mask:0xf bank_mask:0xf
	v_fmac_f32_dpp v85, v77, v201 row_ror:1 row_mask:0xf bank_mask:0xf
	v_fmac_f32_dpp v87, v79, v203 row_ror:1 row_mask:0xf bank_mask:0xf
	v_fmac_f32_dpp v81, v73, v209 row_ror:1 row_mask:0xf bank_mask:0xf
	v_fmac_f32_dpp v83, v75, v211 row_ror:1 row_mask:0xf bank_mask:0xf
	v_pk_mul_f32 v[172:173], v[224:225], s[40:41] op_sel_hi:[1,0]
	v_pk_mul_f32 v[174:175], v[228:229], s[40:41] op_sel_hi:[1,0]
	v_pk_mul_f32 v[172:173], v[224:225], v[172:173]
	v_pk_mul_f32 v[174:175], v[228:229], v[174:175]
	v_pk_fma_f32 v[172:173], v[224:225], v[172:173], v[224:225]
	v_pk_fma_f32 v[174:175], v[228:229], v[174:175], v[228:229]
	v_pk_mul_f32 v[172:173], v[172:173], s[42:43] op_sel_hi:[1,0]
	v_pk_mul_f32 v[174:175], v[174:175], s[42:43] op_sel_hi:[1,0]
	v_pk_mul_f32 v[176:177], v[216:217], v[224:225]
	v_pk_mul_f32 v[178:179], v[220:221], v[228:229]
	v_exp_f32_e32 v172, v172
	v_exp_f32_e32 v173, v173
	v_exp_f32_e32 v174, v174
	v_exp_f32_e32 v175, v175
	v_pk_add_f32 v[172:173], v[172:173], s[44:45] op_sel_hi:[1,0]
	v_pk_add_f32 v[174:175], v[174:175], s[44:45] op_sel_hi:[1,0]
	v_rcp_f32_e32 v172, v172
	v_rcp_f32_e32 v173, v173
	v_rcp_f32_e32 v174, v174
	v_rcp_f32_e32 v175, v175
	s_mov_b32 s26, 0xaa800
	v_lshl_add_u64 v[170:171], v[186:187], 0, s[26:27]
	v_pk_mul_f32 v[176:177], v[176:177], v[172:173]
	v_pk_mul_f32 v[178:179], v[178:179], v[174:175]
	s_and_b64 exec, s[28:29], s[14:15]
	v_cvt_pk_bf16_f32 v176, v176, v177
	v_cvt_pk_bf16_f32 v177, v178, v179
	global_store_dwordx2 v[170:171], v[176:177], off offset:0
	s_mov_b64 exec, s[28:29]
	v_pk_mul_f32 v[172:173], v[226:227], s[40:41] op_sel_hi:[1,0]
	v_pk_mul_f32 v[174:175], v[194:195], s[40:41] op_sel_hi:[1,0]
	v_pk_mul_f32 v[172:173], v[226:227], v[172:173]
	v_pk_mul_f32 v[174:175], v[194:195], v[174:175]
	v_pk_fma_f32 v[172:173], v[226:227], v[172:173], v[226:227]
	v_pk_fma_f32 v[174:175], v[194:195], v[174:175], v[194:195]
	v_pk_mul_f32 v[172:173], v[172:173], s[42:43] op_sel_hi:[1,0]
	v_pk_mul_f32 v[174:175], v[174:175], s[42:43] op_sel_hi:[1,0]
	v_pk_mul_f32 v[176:177], v[218:219], v[226:227]
	v_pk_mul_f32 v[178:179], v[222:223], v[194:195]
	v_exp_f32_e32 v172, v172
	v_exp_f32_e32 v173, v173
	v_exp_f32_e32 v174, v174
	v_exp_f32_e32 v175, v175
	v_pk_add_f32 v[172:173], v[172:173], s[44:45] op_sel_hi:[1,0]
	v_pk_add_f32 v[174:175], v[174:175], s[44:45] op_sel_hi:[1,0]
	v_rcp_f32_e32 v172, v172
	v_rcp_f32_e32 v173, v173
	v_rcp_f32_e32 v174, v174
	v_rcp_f32_e32 v175, v175
	s_mov_b32 s26, 0xc0800
	v_lshl_add_u64 v[170:171], v[186:187], 0, s[26:27]
	v_pk_mul_f32 v[176:177], v[176:177], v[172:173]
	v_pk_mul_f32 v[178:179], v[178:179], v[174:175]
	v_cvt_pk_bf16_f32 v176, v176, v177
	v_cvt_pk_bf16_f32 v177, v178, v179
	global_store_dwordx2 v[170:171], v[176:177], off offset:0
	v_pk_mul_f32 v[172:173], v[88:89], s[40:41] op_sel_hi:[1,0]
	v_pk_mul_f32 v[174:175], v[90:91], s[40:41] op_sel_hi:[1,0]
	v_pk_mul_f32 v[172:173], v[88:89], v[172:173]
	v_pk_mul_f32 v[174:175], v[90:91], v[174:175]
	v_pk_fma_f32 v[172:173], v[88:89], v[172:173], v[88:89]
	v_pk_fma_f32 v[174:175], v[90:91], v[174:175], v[90:91]
	v_pk_mul_f32 v[172:173], v[172:173], s[42:43] op_sel_hi:[1,0]
	v_pk_mul_f32 v[174:175], v[174:175], s[42:43] op_sel_hi:[1,0]
	v_pk_mul_f32 v[176:177], v[92:93], v[88:89]
	v_pk_mul_f32 v[178:179], v[94:95], v[90:91]
	v_exp_f32_e32 v172, v172
	v_exp_f32_e32 v173, v173
	v_exp_f32_e32 v174, v174
	v_exp_f32_e32 v175, v175
	v_pk_add_f32 v[172:173], v[172:173], s[44:45] op_sel_hi:[1,0]
	v_pk_add_f32 v[174:175], v[174:175], s[44:45] op_sel_hi:[1,0]
	v_rcp_f32_e32 v172, v172
	v_rcp_f32_e32 v173, v173
	v_rcp_f32_e32 v174, v174
	v_rcp_f32_e32 v175, v175
	s_mov_b32 s26, 0xd6800
	v_lshl_add_u64 v[170:171], v[186:187], 0, s[26:27]
	v_pk_mul_f32 v[176:177], v[176:177], v[172:173]
	v_pk_mul_f32 v[178:179], v[178:179], v[174:175]
	v_cvt_pk_bf16_f32 v176, v176, v177
	v_cvt_pk_bf16_f32 v177, v178, v179
	global_store_dwordx2 v[170:171], v[176:177], off offset:0
	v_pk_mul_f32 v[172:173], v[80:81], s[40:41] op_sel_hi:[1,0]
; DI unsigned cvtpk(float lo, float hi) { unsigned r; asm volatile("v_cvt_pk_bf16_f32 %0, %1, %2" : "=v"(r) : "v"(lo), "v"(hi)); return r; }
;     DI void operator()(const f32x4 (&acc)[2][2][4][2], const Unit& u, int wr, int wc, int fr_, int fq_) const {
;     ...
;         for (int n = 0; n < 2; ++n) {
;             const int sv = cv0 + 4 * n, sg = FF + cv0 + 4 * n;
;             const f32x4 vp = *(const f32x4*)(cw + sv), vm = *(const f32x4*)(cw + NUP + sv), vn = *(const f32x4*)(cw + 2 * NUP + sv), vb = *(const f32x4*)(cb + sv);
;             const f32x4 gp = *(const f32x4*)(cw + sg), gm = *(const f32x4*)(cw + NUP + sg), gn = *(const f32x4*)(cw + 2 * NUP + sg), gb = *(const f32x4*)(cb + sg);
; #pragma unroll
;             for (int ai = 0; ai < 2; ++ai) {
;                 const int tok0 = u.pm * 248 + (2 * ai + wr) * 62 - 1;
; #pragma unroll
;                 for (int m = 0; m < 4; ++m) { f32x4 zv, zg;
;                     CONV_ONE(acc, ai, 0, n, m, zv, vp, vm, vn); CONV_ONE(acc, ai, 1, n, m, zg, gp, gm, gn);
;                     zv = zv + vb; zg = zg + gb;
;                     float ov[4];
; #pragma unroll
;                     for (int e = 0; e < 4; ++e) { const float x = zg[e]; const float uu = 1.5957691216f * (x + 0.044715f * x * x * x);
;                         ov[e] = zv[e] * x * __builtin_amdgcn_rcpf(1.f + __expf(-uu)); }
;                     if (ROW_VALID(m)) { const int t = tok0 + 16 * m + fr; u32x2 w; w.x = cvtpk(ov[0], ov[1]); w.y = cvtpk(ov[2], ov[3]);
;                         *(u32x2*)(ACT + (size_t)t * FF + cv0 + 4 * n) = w; }
;                     __builtin_amdgcn_sched_barrier(0); }
	v_pk_mul_f32 v[174:175], v[82:83], s[40:41] op_sel_hi:[1,0]
	v_pk_mul_f32 v[172:173], v[80:81], v[172:173]
	v_pk_mul_f32 v[174:175], v[82:83], v[174:175]
	v_pk_fma_f32 v[172:173], v[80:81], v[172:173], v[80:81]
	v_pk_fma_f32 v[174:175], v[82:83], v[174:175], v[82:83]
	v_pk_mul_f32 v[172:173], v[172:173], s[42:43] op_sel_hi:[1,0]
	v_pk_mul_f32 v[174:175], v[174:175], s[42:43] op_sel_hi:[1,0]
	v_pk_mul_f32 v[176:177], v[84:85], v[80:81]
	v_pk_mul_f32 v[178:179], v[86:87], v[82:83]
	v_exp_f32_e32 v172, v172
	v_exp_f32_e32 v173, v173
	v_exp_f32_e32 v174, v174
	v_exp_f32_e32 v175, v175
	v_pk_add_f32 v[172:173], v[172:173], s[44:45] op_sel_hi:[1,0]
	v_pk_add_f32 v[174:175], v[174:175], s[44:45] op_sel_hi:[1,0]
	v_rcp_f32_e32 v172, v172
	v_rcp_f32_e32 v173, v173
	v_rcp_f32_e32 v174, v174
	v_rcp_f32_e32 v175, v175
	s_mov_b32 s26, 0xec800
	v_lshl_add_u64 v[170:171], v[186:187], 0, s[26:27]
	v_pk_mul_f32 v[176:177], v[176:177], v[172:173]
	v_pk_mul_f32 v[178:179], v[178:179], v[174:175]
	s_and_b64 exec, s[28:29], s[24:25]
	v_cvt_pk_bf16_f32 v176, v176, v177
	v_cvt_pk_bf16_f32 v177, v178, v179
	global_store_dwordx2 v[170:171], v[176:177], off offset:0
	s_mov_b64 exec, s[28:29]
	global_load_dwordx4 v[96:99], v188, s[18:19] offset:16
	global_load_dwordx4 v[100:103], v188, s[88:89] offset:16
	global_load_dwordx4 v[104:107], v188, s[90:91] offset:16
	global_load_dwordx4 v[108:111], v188, s[20:21] offset:16
	global_load_dwordx4 v[112:115], v189, s[18:19] offset:16
	global_load_dwordx4 v[116:119], v189, s[88:89] offset:16
	global_load_dwordx4 v[120:123], v189, s[90:91] offset:16
	global_load_dwordx4 v[124:127], v189, s[20:21] offset:16
	s_waitcnt vmcnt(0)
	v_cndmask_b32_e64 v200, 0, v96, s[10:11]
	v_cndmask_b32_e64 v204, 0, v104, s[12:13]
	v_cndmask_b32_e64 v208, 0, v112, s[10:11]
	v_cndmask_b32_e64 v212, 0, v120, s[12:13]
	v_cndmask_b32_e64 v201, 0, v97, s[10:11]
	v_cndmask_b32_e64 v205, 0, v105, s[12:13]
	v_cndmask_b32_e64 v209, 0, v113, s[10:11]
	v_cndmask_b32_e64 v213, 0, v121, s[12:13]
	v_cndmask_b32_e64 v202, 0, v98, s[10:11]
	v_cndmask_b32_e64 v206, 0, v106, s[12:13]
	v_cndmask_b32_e64 v210, 0, v114, s[10:11]
	v_cndmask_b32_e64 v214, 0, v122, s[12:13]
	v_cndmask_b32_e64 v203, 0, v99, s[10:11]
	v_cndmask_b32_e64 v207, 0, v107, s[12:13]
	v_cndmask_b32_e64 v211, 0, v115, s[10:11]
	v_cndmask_b32_e64 v215, 0, v123, s[12:13]
	v_pk_fma_f32 v[216:217], v[60:61], v[100:101], v[108:109]
	v_pk_fma_f32 v[218:219], v[52:53], v[100:101], v[108:109]
	v_pk_fma_f32 v[220:221], v[62:63], v[102:103], v[110:111]
	v_pk_fma_f32 v[222:223], v[54:55], v[102:103], v[110:111]
	v_pk_fma_f32 v[224:225], v[56:57], v[116:117], v[124:125]
	v_pk_fma_f32 v[226:227], v[48:49], v[116:117], v[124:125]
	v_pk_fma_f32 v[228:229], v[58:59], v[118:119], v[126:127]
	v_pk_fma_f32 v[194:195], v[50:51], v[118:119], v[126:127]
	v_fmac_f32_dpp v216, v60, v96 row_shr:1 row_mask:0xf bank_mask:0xf
	v_fmac_f32_dpp v218, v52, v96 row_shr:1 row_mask:0xf bank_mask:0xf
	v_fmac_f32_dpp v220, v62, v98 row_shr:1 row_mask:0xf bank_mask:0xf
	v_fmac_f32_dpp v222, v54, v98 row_shr:1 row_mask:0xf bank_mask:0xf
	v_fmac_f32_dpp v224, v56, v112 row_shr:1 row_mask:0xf bank_mask:0xf
	v_fmac_f32_dpp v226, v48, v112 row_shr:1 row_mask:0xf bank_mask:0xf
	v_fmac_f32_dpp v228, v58, v114 row_shr:1 row_mask:0xf bank_mask:0xf
	v_fmac_f32_dpp v194, v50, v114 row_shr:1 row_mask:0xf bank_mask:0xf
	v_fmac_f32_dpp v216, v60, v104 row_shl:1 row_mask:0xf bank_mask:0xf
	v_fmac_f32_dpp v218, v52, v104 row_shl:1 row_mask:0xf bank_mask:0xf
	v_fmac_f32_dpp v220, v62, v106 row_shl:1 row_mask:0xf bank_mask:0xf
	v_fmac_f32_dpp v222, v54, v106 row_shl:1 row_mask:0xf bank_mask:0xf
	v_fmac_f32_dpp v224, v56, v120 row_shl:1 row_mask:0xf bank_mask:0xf
	v_fmac_f32_dpp v226, v48, v120 row_shl:1 row_mask:0xf bank_mask:0xf
	v_fmac_f32_dpp v228, v58, v122 row_shl:1 row_mask:0xf bank_mask:0xf
	v_fmac_f32_dpp v194, v50, v122 row_shl:1 row_mask:0xf bank_mask:0xf
	v_fmac_f32_dpp v216, v52, v204 row_ror:15 row_mask:0xf bank_mask:0xf
	v_fmac_f32_dpp v218, v60, v200 row_ror:1 row_mask:0xf bank_mask:0xf
	v_fmac_f32_dpp v220, v54, v206 row_ror:15 row_mask:0xf bank_mask:0xf
	v_fmac_f32_dpp v222, v62, v202 row_ror:1 row_mask:0xf bank_mask:0xf
	v_fmac_f32_dpp v224, v48, v212 row_ror:15 row_mask:0xf bank_mask:0xf
	v_fmac_f32_dpp v226, v56, v208 row_ror:1 row_mask:0xf bank_mask:0xf
	v_fmac_f32_dpp v228, v50, v214 row_ror:15 row_mask:0xf bank_mask:0xf
	v_fmac_f32_dpp v194, v58, v210 row_ror:1 row_mask:0xf bank_mask:0xf
	v_fmac_f32_dpp v217, v61, v97 row_shr:1 row_mask:0xf bank_mask:0xf
	v_fmac_f32_dpp v218, v44, v204 row_ror:15 row_mask:0xf bank_mask:0xf
	v_fmac_f32_dpp v221, v63, v99 row_shr:1 row_mask:0xf bank_mask:0xf
	v_fmac_f32_dpp v222, v46, v206 row_ror:15 row_mask:0xf bank_mask:0xf
	v_fmac_f32_dpp v225, v57, v113 row_shr:1 row_mask:0xf bank_mask:0xf
	v_fmac_f32_dpp v226, v40, v212 row_ror:15 row_mask:0xf bank_mask:0xf
	v_fmac_f32_dpp v229, v59, v115 row_shr:1 row_mask:0xf bank_mask:0xf
	v_fmac_f32_dpp v194, v42, v214 row_ror:15 row_mask:0xf bank_mask:0xf
	v_fmac_f32_dpp v217, v61, v105 row_shl:1 row_mask:0xf bank_mask:0xf
	v_fmac_f32_dpp v219, v53, v97 row_shr:1 row_mask:0xf bank_mask:0xf
	v_fmac_f32_dpp v221, v63, v107 row_shl:1 row_mask:0xf bank_mask:0xf
	v_fmac_f32_dpp v223, v55, v99 row_shr:1 row_mask:0xf bank_mask:0xf
	v_fmac_f32_dpp v225, v57, v121 row_shl:1 row_mask:0xf bank_mask:0xf
	v_fmac_f32_dpp v227, v49, v113 row_shr:1 row_mask:0xf bank_mask:0xf
	v_fmac_f32_dpp v229, v59, v123 row_shl:1 row_mask:0xf bank_mask:0xf
	v_fmac_f32_dpp v195, v51, v115 row_shr:1 row_mask:0xf bank_mask:0xf
	v_fmac_f32_dpp v217, v53, v205 row_ror:15 row_mask:0xf bank_mask:0xf
;     DI void operator()(const f32x4 (&acc)[2][2][4][2], const Unit& u, int wr, int wc, int fr_, int fq_) const {
;     ...
;             for (int ai = 0; ai < 2; ++ai) {
;                 const int tok0 = u.pm * 248 + (2 * ai + wr) * 62 - 1;
; #pragma unroll
;                 for (int m = 0; m < 4; ++m) { f32x4 zv, zg;
;                     CONV_ONE(acc, ai, 0, n, m, zv, vp, vm, vn); CONV_ONE(acc, ai, 1, n, m, zg, gp, gm, gn);
;                     zv = zv + vb; zg = zg + gb;
;                     float ov[4];
; #pragma unroll
;                     for (int e = 0; e < 4; ++e) { const float x = zg[e]; const float uu = 1.5957691216f * (x + 0.044715f * x * x * x);
;                         ov[e] = zv[e] * x * __builtin_amdgcn_rcpf(1.f + __expf(-uu)); }
	v_fmac_f32_dpp v219, v53, v105 row_shl:1 row_mask:0xf bank_mask:0xf
	v_fmac_f32_dpp v221, v55, v207 row_ror:15 row_mask:0xf bank_mask:0xf
	v_fmac_f32_dpp v223, v55, v107 row_shl:1 row_mask:0xf bank_mask:0xf
	v_fmac_f32_dpp v225, v49, v213 row_ror:15 row_mask:0xf bank_mask:0xf
	v_fmac_f32_dpp v227, v49, v121 row_shl:1 row_mask:0xf bank_mask:0xf
	v_fmac_f32_dpp v229, v51, v215 row_ror:15 row_mask:0xf bank_mask:0xf
	v_fmac_f32_dpp v195, v51, v123 row_shl:1 row_mask:0xf bank_mask:0xf
	v_fmac_f32_dpp v219, v61, v201 row_ror:1 row_mask:0xf bank_mask:0xf
	v_fmac_f32_dpp v223, v63, v203 row_ror:1 row_mask:0xf bank_mask:0xf
	v_fmac_f32_dpp v227, v57, v209 row_ror:1 row_mask:0xf bank_mask:0xf
	v_fmac_f32_dpp v195, v59, v211 row_ror:1 row_mask:0xf bank_mask:0xf
	v_fmac_f32_dpp v219, v45, v205 row_ror:15 row_mask:0xf bank_mask:0xf
	v_fmac_f32_dpp v223, v47, v207 row_ror:15 row_mask:0xf bank_mask:0xf
	v_fmac_f32_dpp v227, v41, v213 row_ror:15 row_mask:0xf bank_mask:0xf
	v_fmac_f32_dpp v195, v43, v215 row_ror:15 row_mask:0xf bank_mask:0xf
	v_pk_fma_f32 v[60:61], v[44:45], v[100:101], v[108:109]
	v_pk_fma_f32 v[62:63], v[46:47], v[102:103], v[110:111]
	v_pk_fma_f32 v[56:57], v[40:41], v[116:117], v[124:125]
	v_pk_fma_f32 v[58:59], v[42:43], v[118:119], v[126:127]
	v_fmac_f32_dpp v60, v44, v96 row_shr:1 row_mask:0xf bank_mask:0xf
	v_fmac_f32_dpp v62, v46, v98 row_shr:1 row_mask:0xf bank_mask:0xf
	v_fmac_f32_dpp v56, v40, v112 row_shr:1 row_mask:0xf bank_mask:0xf
	v_fmac_f32_dpp v58, v42, v114 row_shr:1 row_mask:0xf bank_mask:0xf
	v_fmac_f32_dpp v60, v44, v104 row_shl:1 row_mask:0xf bank_mask:0xf
	v_fmac_f32_dpp v62, v46, v106 row_shl:1 row_mask:0xf bank_mask:0xf
	v_fmac_f32_dpp v56, v40, v120 row_shl:1 row_mask:0xf bank_mask:0xf
	v_fmac_f32_dpp v58, v42, v122 row_shl:1 row_mask:0xf bank_mask:0xf
	v_fmac_f32_dpp v60, v52, v200 row_ror:1 row_mask:0xf bank_mask:0xf
	v_fmac_f32_dpp v62, v54, v202 row_ror:1 row_mask:0xf bank_mask:0xf
	v_fmac_f32_dpp v56, v48, v208 row_ror:1 row_mask:0xf bank_mask:0xf
	v_fmac_f32_dpp v58, v50, v210 row_ror:1 row_mask:0xf bank_mask:0xf
	v_fmac_f32_dpp v60, v36, v204 row_ror:15 row_mask:0xf bank_mask:0xf
	v_fmac_f32_dpp v62, v38, v206 row_ror:15 row_mask:0xf bank_mask:0xf
	v_fmac_f32_dpp v56, v32, v212 row_ror:15 row_mask:0xf bank_mask:0xf
	v_fmac_f32_dpp v58, v34, v214 row_ror:15 row_mask:0xf bank_mask:0xf
	v_fmac_f32_dpp v61, v45, v97 row_shr:1 row_mask:0xf bank_mask:0xf
	v_fmac_f32_dpp v63, v47, v99 row_shr:1 row_mask:0xf bank_mask:0xf
	v_fmac_f32_dpp v57, v41, v113 row_shr:1 row_mask:0xf bank_mask:0xf
	v_fmac_f32_dpp v59, v43, v115 row_shr:1 row_mask:0xf bank_mask:0xf
	v_fmac_f32_dpp v61, v45, v105 row_shl:1 row_mask:0xf bank_mask:0xf
	v_fmac_f32_dpp v63, v47, v107 row_shl:1 row_mask:0xf bank_mask:0xf
	v_fmac_f32_dpp v57, v41, v121 row_shl:1 row_mask:0xf bank_mask:0xf
	v_fmac_f32_dpp v59, v43, v123 row_shl:1 row_mask:0xf bank_mask:0xf
	v_fmac_f32_dpp v61, v53, v201 row_ror:1 row_mask:0xf bank_mask:0xf
	v_fmac_f32_dpp v63, v55, v203 row_ror:1 row_mask:0xf bank_mask:0xf
	v_fmac_f32_dpp v57, v49, v209 row_ror:1 row_mask:0xf bank_mask:0xf
	v_fmac_f32_dpp v59, v51, v211 row_ror:1 row_mask:0xf bank_mask:0xf
	v_fmac_f32_dpp v61, v37, v205 row_ror:15 row_mask:0xf bank_mask:0xf
	v_fmac_f32_dpp v63, v39, v207 row_ror:15 row_mask:0xf bank_mask:0xf
	v_fmac_f32_dpp v57, v33, v213 row_ror:15 row_mask:0xf bank_mask:0xf
	v_fmac_f32_dpp v59, v35, v215 row_ror:15 row_mask:0xf bank_mask:0xf
	v_pk_fma_f32 v[52:53], v[36:37], v[100:101], v[108:109]
	v_pk_fma_f32 v[54:55], v[38:39], v[102:103], v[110:111]
	v_pk_fma_f32 v[48:49], v[32:33], v[116:117], v[124:125]
	v_pk_fma_f32 v[50:51], v[34:35], v[118:119], v[126:127]
	v_fmac_f32_dpp v52, v36, v96 row_shr:1 row_mask:0xf bank_mask:0xf
	v_fmac_f32_dpp v54, v38, v98 row_shr:1 row_mask:0xf bank_mask:0xf
	v_fmac_f32_dpp v48, v32, v112 row_shr:1 row_mask:0xf bank_mask:0xf
	v_fmac_f32_dpp v50, v34, v114 row_shr:1 row_mask:0xf bank_mask:0xf
	v_fmac_f32_dpp v52, v36, v104 row_shl:1 row_mask:0xf bank_mask:0xf
	v_fmac_f32_dpp v54, v38, v106 row_shl:1 row_mask:0xf bank_mask:0xf
	v_fmac_f32_dpp v48, v32, v120 row_shl:1 row_mask:0xf bank_mask:0xf
	v_fmac_f32_dpp v50, v34, v122 row_shl:1 row_mask:0xf bank_mask:0xf
	v_fmac_f32_dpp v52, v44, v200 row_ror:1 row_mask:0xf bank_mask:0xf
	v_fmac_f32_dpp v54, v46, v202 row_ror:1 row_mask:0xf bank_mask:0xf
	v_fmac_f32_dpp v48, v40, v208 row_ror:1 row_mask:0xf bank_mask:0xf
	v_fmac_f32_dpp v50, v42, v210 row_ror:1 row_mask:0xf bank_mask:0xf
	v_fmac_f32_dpp v53, v37, v97 row_shr:1 row_mask:0xf bank_mask:0xf
	v_fmac_f32_dpp v55, v39, v99 row_shr:1 row_mask:0xf bank_mask:0xf
	v_fmac_f32_dpp v49, v33, v113 row_shr:1 row_mask:0xf bank_mask:0xf
	v_fmac_f32_dpp v51, v35, v115 row_shr:1 row_mask:0xf bank_mask:0xf
	v_fmac_f32_dpp v53, v37, v105 row_shl:1 row_mask:0xf bank_mask:0xf
	v_fmac_f32_dpp v55, v39, v107 row_shl:1 row_mask:0xf bank_mask:0xf
	v_fmac_f32_dpp v49, v33, v121 row_shl:1 row_mask:0xf bank_mask:0xf
	v_fmac_f32_dpp v51, v35, v123 row_shl:1 row_mask:0xf bank_mask:0xf
	v_fmac_f32_dpp v53, v45, v201 row_ror:1 row_mask:0xf bank_mask:0xf
	v_fmac_f32_dpp v55, v47, v203 row_ror:1 row_mask:0xf bank_mask:0xf
	v_fmac_f32_dpp v49, v41, v209 row_ror:1 row_mask:0xf bank_mask:0xf
	v_fmac_f32_dpp v51, v43, v211 row_ror:1 row_mask:0xf bank_mask:0xf
	v_pk_mul_f32 v[172:173], v[224:225], s[40:41] op_sel_hi:[1,0]
	v_pk_mul_f32 v[174:175], v[228:229], s[40:41] op_sel_hi:[1,0]
	v_pk_mul_f32 v[172:173], v[224:225], v[172:173]
	v_pk_mul_f32 v[174:175], v[228:229], v[174:175]
	v_pk_fma_f32 v[172:173], v[224:225], v[172:173], v[224:225]
	v_pk_fma_f32 v[174:175], v[228:229], v[174:175], v[228:229]
; DI unsigned cvtpk(float lo, float hi) { unsigned r; asm volatile("v_cvt_pk_bf16_f32 %0, %1, %2" : "=v"(r) : "v"(lo), "v"(hi)); return r; }
;     DI void operator()(const f32x4 (&acc)[2][2][4][2], const Unit& u, int wr, int wc, int fr_, int fq_) const {
;     ...
;                 for (int m = 0; m < 4; ++m) { f32x4 zv, zg;
;                     CONV_ONE(acc, ai, 0, n, m, zv, vp, vm, vn); CONV_ONE(acc, ai, 1, n, m, zg, gp, gm, gn);
;                     zv = zv + vb; zg = zg + gb;
;                     float ov[4];
; #pragma unroll
;                     for (int e = 0; e < 4; ++e) { const float x = zg[e]; const float uu = 1.5957691216f * (x + 0.044715f * x * x * x);
;                         ov[e] = zv[e] * x * __builtin_amdgcn_rcpf(1.f + __expf(-uu)); }
;                     if (ROW_VALID(m)) { const int t = tok0 + 16 * m + fr; u32x2 w; w.x = cvtpk(ov[0], ov[1]); w.y = cvtpk(ov[2], ov[3]);
;                         *(u32x2*)(ACT + (size_t)t * FF + cv0 + 4 * n) = w; }
;                     __builtin_amdgcn_sched_barrier(0); }
	v_pk_mul_f32 v[172:173], v[172:173], s[42:43] op_sel_hi:[1,0]
	v_pk_mul_f32 v[174:175], v[174:175], s[42:43] op_sel_hi:[1,0]
	v_pk_mul_f32 v[176:177], v[216:217], v[224:225]
	v_pk_mul_f32 v[178:179], v[220:221], v[228:229]
	v_exp_f32_e32 v172, v172
	v_exp_f32_e32 v173, v173
	v_exp_f32_e32 v174, v174
	v_exp_f32_e32 v175, v175
	v_pk_add_f32 v[172:173], v[172:173], s[44:45] op_sel_hi:[1,0]
	v_pk_add_f32 v[174:175], v[174:175], s[44:45] op_sel_hi:[1,0]
	v_rcp_f32_e32 v172, v172
	v_rcp_f32_e32 v173, v173
	v_rcp_f32_e32 v174, v174
	v_rcp_f32_e32 v175, v175
	s_mov_b32 s26, 0x0
	v_lshl_add_u64 v[170:171], v[186:187], 0, s[26:27]
	v_pk_mul_f32 v[176:177], v[176:177], v[172:173]
	v_pk_mul_f32 v[178:179], v[178:179], v[174:175]
	s_and_b64 exec, s[28:29], s[14:15]
	v_cvt_pk_bf16_f32 v176, v176, v177
	v_cvt_pk_bf16_f32 v177, v178, v179
	global_store_dwordx2 v[170:171], v[176:177], off offset:8
	s_mov_b64 exec, s[28:29]
	v_pk_mul_f32 v[172:173], v[226:227], s[40:41] op_sel_hi:[1,0]
	v_pk_mul_f32 v[174:175], v[194:195], s[40:41] op_sel_hi:[1,0]
	v_pk_mul_f32 v[172:173], v[226:227], v[172:173]
	v_pk_mul_f32 v[174:175], v[194:195], v[174:175]
	v_pk_fma_f32 v[172:173], v[226:227], v[172:173], v[226:227]
	v_pk_fma_f32 v[174:175], v[194:195], v[174:175], v[194:195]
	v_pk_mul_f32 v[172:173], v[172:173], s[42:43] op_sel_hi:[1,0]
	v_pk_mul_f32 v[174:175], v[174:175], s[42:43] op_sel_hi:[1,0]
	v_pk_mul_f32 v[176:177], v[218:219], v[226:227]
	v_pk_mul_f32 v[178:179], v[222:223], v[194:195]
	v_exp_f32_e32 v172, v172
	v_exp_f32_e32 v173, v173
	v_exp_f32_e32 v174, v174
	v_exp_f32_e32 v175, v175
	v_pk_add_f32 v[172:173], v[172:173], s[44:45] op_sel_hi:[1,0]
	v_pk_add_f32 v[174:175], v[174:175], s[44:45] op_sel_hi:[1,0]
	v_rcp_f32_e32 v172, v172
	v_rcp_f32_e32 v173, v173
	v_rcp_f32_e32 v174, v174
	v_rcp_f32_e32 v175, v175
	s_mov_b32 s26, 0x16000
	v_lshl_add_u64 v[170:171], v[186:187], 0, s[26:27]
	v_pk_mul_f32 v[176:177], v[176:177], v[172:173]
	v_pk_mul_f32 v[178:179], v[178:179], v[174:175]
	v_cvt_pk_bf16_f32 v176, v176, v177
	v_cvt_pk_bf16_f32 v177, v178, v179
	global_store_dwordx2 v[170:171], v[176:177], off offset:8
	v_pk_mul_f32 v[172:173], v[56:57], s[40:41] op_sel_hi:[1,0]
	v_pk_mul_f32 v[174:175], v[58:59], s[40:41] op_sel_hi:[1,0]
	v_pk_mul_f32 v[172:173], v[56:57], v[172:173]
	v_pk_mul_f32 v[174:175], v[58:59], v[174:175]
	v_pk_fma_f32 v[172:173], v[56:57], v[172:173], v[56:57]
	v_pk_fma_f32 v[174:175], v[58:59], v[174:175], v[58:59]
	v_pk_mul_f32 v[172:173], v[172:173], s[42:43] op_sel_hi:[1,0]
	v_pk_mul_f32 v[174:175], v[174:175], s[42:43] op_sel_hi:[1,0]
	v_pk_mul_f32 v[176:177], v[60:61], v[56:57]
	v_pk_mul_f32 v[178:179], v[62:63], v[58:59]
	v_exp_f32_e32 v172, v172
	v_exp_f32_e32 v173, v173
	v_exp_f32_e32 v174, v174
	v_exp_f32_e32 v175, v175
	v_pk_add_f32 v[172:173], v[172:173], s[44:45] op_sel_hi:[1,0]
	v_pk_add_f32 v[174:175], v[174:175], s[44:45] op_sel_hi:[1,0]
	v_rcp_f32_e32 v172, v172
	v_rcp_f32_e32 v173, v173
	v_rcp_f32_e32 v174, v174
	v_rcp_f32_e32 v175, v175
	s_mov_b32 s26, 0x2c000
	v_lshl_add_u64 v[170:171], v[186:187], 0, s[26:27]
	v_pk_mul_f32 v[176:177], v[176:177], v[172:173]
	v_pk_mul_f32 v[178:179], v[178:179], v[174:175]
	v_cvt_pk_bf16_f32 v176, v176, v177
	v_cvt_pk_bf16_f32 v177, v178, v179
	global_store_dwordx2 v[170:171], v[176:177], off offset:8
	v_pk_mul_f32 v[172:173], v[48:49], s[40:41] op_sel_hi:[1,0]
	v_pk_mul_f32 v[174:175], v[50:51], s[40:41] op_sel_hi:[1,0]
	v_pk_mul_f32 v[172:173], v[48:49], v[172:173]
	v_pk_mul_f32 v[174:175], v[50:51], v[174:175]
	v_pk_fma_f32 v[172:173], v[48:49], v[172:173], v[48:49]
	v_pk_fma_f32 v[174:175], v[50:51], v[174:175], v[50:51]
	v_pk_mul_f32 v[172:173], v[172:173], s[42:43] op_sel_hi:[1,0]
	v_pk_mul_f32 v[174:175], v[174:175], s[42:43] op_sel_hi:[1,0]
	v_pk_mul_f32 v[176:177], v[52:53], v[48:49]
	v_pk_mul_f32 v[178:179], v[54:55], v[50:51]
	v_exp_f32_e32 v172, v172
	v_exp_f32_e32 v173, v173
	v_exp_f32_e32 v174, v174
	v_exp_f32_e32 v175, v175
	v_pk_add_f32 v[172:173], v[172:173], s[44:45] op_sel_hi:[1,0]
	v_pk_add_f32 v[174:175], v[174:175], s[44:45] op_sel_hi:[1,0]
	v_rcp_f32_e32 v172, v172
	v_rcp_f32_e32 v173, v173
	v_rcp_f32_e32 v174, v174
	v_rcp_f32_e32 v175, v175
	s_mov_b32 s26, 0x42000
	v_lshl_add_u64 v[170:171], v[186:187], 0, s[26:27]
	v_pk_mul_f32 v[176:177], v[176:177], v[172:173]
	v_pk_mul_f32 v[178:179], v[178:179], v[174:175]
	s_and_b64 exec, s[28:29], s[24:25]
	v_cvt_pk_bf16_f32 v176, v176, v177
	v_cvt_pk_bf16_f32 v177, v178, v179
	global_store_dwordx2 v[170:171], v[176:177], off offset:8
	s_mov_b64 exec, s[28:29]
	v_pk_fma_f32 v[216:217], v[28:29], v[100:101], v[108:109]
	v_pk_fma_f32 v[218:219], v[20:21], v[100:101], v[108:109]
	v_pk_fma_f32 v[220:221], v[30:31], v[102:103], v[110:111]
	v_pk_fma_f32 v[222:223], v[22:23], v[102:103], v[110:111]
	v_pk_fma_f32 v[224:225], v[24:25], v[116:117], v[124:125]
	v_pk_fma_f32 v[226:227], v[16:17], v[116:117], v[124:125]
	v_pk_fma_f32 v[228:229], v[26:27], v[118:119], v[126:127]
	v_pk_fma_f32 v[194:195], v[18:19], v[118:119], v[126:127]
	v_fmac_f32_dpp v216, v28, v96 row_shr:1 row_mask:0xf bank_mask:0xf
	v_fmac_f32_dpp v218, v20, v96 row_shr:1 row_mask:0xf bank_mask:0xf
	v_fmac_f32_dpp v220, v30, v98 row_shr:1 row_mask:0xf bank_mask:0xf
	v_fmac_f32_dpp v222, v22, v98 row_shr:1 row_mask:0xf bank_mask:0xf
	v_fmac_f32_dpp v224, v24, v112 row_shr:1 row_mask:0xf bank_mask:0xf
	v_fmac_f32_dpp v226, v16, v112 row_shr:1 row_mask:0xf bank_mask:0xf
	v_fmac_f32_dpp v228, v26, v114 row_shr:1 row_mask:0xf bank_mask:0xf
	v_fmac_f32_dpp v194, v18, v114 row_shr:1 row_mask:0xf bank_mask:0xf
	v_fmac_f32_dpp v216, v28, v104 row_shl:1 row_mask:0xf bank_mask:0xf
;     DI void operator()(const f32x4 (&acc)[2][2][4][2], const Unit& u, int wr, int wc, int fr_, int fq_) const {
;     ...
;             for (int ai = 0; ai < 2; ++ai) {
;                 const int tok0 = u.pm * 248 + (2 * ai + wr) * 62 - 1;
; #pragma unroll
;                 for (int m = 0; m < 4; ++m) { f32x4 zv, zg;
;                     CONV_ONE(acc, ai, 0, n, m, zv, vp, vm, vn); CONV_ONE(acc, ai, 1, n, m, zg, gp, gm, gn);
;                     zv = zv + vb; zg = zg + gb;
	v_fmac_f32_dpp v218, v20, v104 row_shl:1 row_mask:0xf bank_mask:0xf
	v_fmac_f32_dpp v220, v30, v106 row_shl:1 row_mask:0xf bank_mask:0xf
	v_fmac_f32_dpp v222, v22, v106 row_shl:1 row_mask:0xf bank_mask:0xf
	v_fmac_f32_dpp v224, v24, v120 row_shl:1 row_mask:0xf bank_mask:0xf
	v_fmac_f32_dpp v226, v16, v120 row_shl:1 row_mask:0xf bank_mask:0xf
	v_fmac_f32_dpp v228, v26, v122 row_shl:1 row_mask:0xf bank_mask:0xf
	v_fmac_f32_dpp v194, v18, v122 row_shl:1 row_mask:0xf bank_mask:0xf
	v_fmac_f32_dpp v216, v20, v204 row_ror:15 row_mask:0xf bank_mask:0xf
	v_fmac_f32_dpp v218, v28, v200 row_ror:1 row_mask:0xf bank_mask:0xf
	v_fmac_f32_dpp v220, v22, v206 row_ror:15 row_mask:0xf bank_mask:0xf
	v_fmac_f32_dpp v222, v30, v202 row_ror:1 row_mask:0xf bank_mask:0xf
	v_fmac_f32_dpp v224, v16, v212 row_ror:15 row_mask:0xf bank_mask:0xf
	v_fmac_f32_dpp v226, v24, v208 row_ror:1 row_mask:0xf bank_mask:0xf
	v_fmac_f32_dpp v228, v18, v214 row_ror:15 row_mask:0xf bank_mask:0xf
	v_fmac_f32_dpp v194, v26, v210 row_ror:1 row_mask:0xf bank_mask:0xf
	v_fmac_f32_dpp v217, v29, v97 row_shr:1 row_mask:0xf bank_mask:0xf
	v_fmac_f32_dpp v218, v12, v204 row_ror:15 row_mask:0xf bank_mask:0xf
	v_fmac_f32_dpp v221, v31, v99 row_shr:1 row_mask:0xf bank_mask:0xf
	v_fmac_f32_dpp v222, v14, v206 row_ror:15 row_mask:0xf bank_mask:0xf
	v_fmac_f32_dpp v225, v25, v113 row_shr:1 row_mask:0xf bank_mask:0xf
	v_fmac_f32_dpp v226, v8, v212 row_ror:15 row_mask:0xf bank_mask:0xf
	v_fmac_f32_dpp v229, v27, v115 row_shr:1 row_mask:0xf bank_mask:0xf
	v_fmac_f32_dpp v194, v10, v214 row_ror:15 row_mask:0xf bank_mask:0xf
	v_fmac_f32_dpp v217, v29, v105 row_shl:1 row_mask:0xf bank_mask:0xf
	v_fmac_f32_dpp v219, v21, v97 row_shr:1 row_mask:0xf bank_mask:0xf
	v_fmac_f32_dpp v221, v31, v107 row_shl:1 row_mask:0xf bank_mask:0xf
	v_fmac_f32_dpp v223, v23, v99 row_shr:1 row_mask:0xf bank_mask:0xf
	v_fmac_f32_dpp v225, v25, v121 row_shl:1 row_mask:0xf bank_mask:0xf
	v_fmac_f32_dpp v227, v17, v113 row_shr:1 row_mask:0xf bank_mask:0xf
	v_fmac_f32_dpp v229, v27, v123 row_shl:1 row_mask:0xf bank_mask:0xf
	v_fmac_f32_dpp v195, v19, v115 row_shr:1 row_mask:0xf bank_mask:0xf
	v_fmac_f32_dpp v217, v21, v205 row_ror:15 row_mask:0xf bank_mask:0xf
	v_fmac_f32_dpp v219, v21, v105 row_shl:1 row_mask:0xf bank_mask:0xf
	v_fmac_f32_dpp v221, v23, v207 row_ror:15 row_mask:0xf bank_mask:0xf
	v_fmac_f32_dpp v223, v23, v107 row_shl:1 row_mask:0xf bank_mask:0xf
	v_fmac_f32_dpp v225, v17, v213 row_ror:15 row_mask:0xf bank_mask:0xf
	v_fmac_f32_dpp v227, v17, v121 row_shl:1 row_mask:0xf bank_mask:0xf
	v_fmac_f32_dpp v229, v19, v215 row_ror:15 row_mask:0xf bank_mask:0xf
	v_fmac_f32_dpp v195, v19, v123 row_shl:1 row_mask:0xf bank_mask:0xf
	v_fmac_f32_dpp v219, v29, v201 row_ror:1 row_mask:0xf bank_mask:0xf
	v_fmac_f32_dpp v223, v31, v203 row_ror:1 row_mask:0xf bank_mask:0xf
	v_fmac_f32_dpp v227, v25, v209 row_ror:1 row_mask:0xf bank_mask:0xf
	v_fmac_f32_dpp v195, v27, v211 row_ror:1 row_mask:0xf bank_mask:0xf
	v_fmac_f32_dpp v219, v13, v205 row_ror:15 row_mask:0xf bank_mask:0xf
	v_fmac_f32_dpp v223, v15, v207 row_ror:15 row_mask:0xf bank_mask:0xf
	v_fmac_f32_dpp v227, v9, v213 row_ror:15 row_mask:0xf bank_mask:0xf
	v_fmac_f32_dpp v195, v11, v215 row_ror:15 row_mask:0xf bank_mask:0xf
	v_pk_fma_f32 v[28:29], v[12:13], v[100:101], v[108:109]
	v_pk_fma_f32 v[30:31], v[14:15], v[102:103], v[110:111]
	v_pk_fma_f32 v[24:25], v[8:9], v[116:117], v[124:125]
	v_pk_fma_f32 v[26:27], v[10:11], v[118:119], v[126:127]
	v_fmac_f32_dpp v28, v12, v96 row_shr:1 row_mask:0xf bank_mask:0xf
	v_fmac_f32_dpp v30, v14, v98 row_shr:1 row_mask:0xf bank_mask:0xf
	v_fmac_f32_dpp v24, v8, v112 row_shr:1 row_mask:0xf bank_mask:0xf
	v_fmac_f32_dpp v26, v10, v114 row_shr:1 row_mask:0xf bank_mask:0xf
	v_fmac_f32_dpp v28, v12, v104 row_shl:1 row_mask:0xf bank_mask:0xf
	v_fmac_f32_dpp v30, v14, v106 row_shl:1 row_mask:0xf bank_mask:0xf
	v_fmac_f32_dpp v24, v8, v120 row_shl:1 row_mask:0xf bank_mask:0xf
	v_fmac_f32_dpp v26, v10, v122 row_shl:1 row_mask:0xf bank_mask:0xf
	v_fmac_f32_dpp v28, v20, v200 row_ror:1 row_mask:0xf bank_mask:0xf
	v_fmac_f32_dpp v30, v22, v202 row_ror:1 row_mask:0xf bank_mask:0xf
	v_fmac_f32_dpp v24, v16, v208 row_ror:1 row_mask:0xf bank_mask:0xf
	v_fmac_f32_dpp v26, v18, v210 row_ror:1 row_mask:0xf bank_mask:0xf
	v_fmac_f32_dpp v28, v4, v204 row_ror:15 row_mask:0xf bank_mask:0xf
	v_fmac_f32_dpp v30, v6, v206 row_ror:15 row_mask:0xf bank_mask:0xf
	v_fmac_f32_dpp v24, v0, v212 row_ror:15 row_mask:0xf bank_mask:0xf
	v_fmac_f32_dpp v26, v2, v214 row_ror:15 row_mask:0xf bank_mask:0xf
	v_fmac_f32_dpp v29, v13, v97 row_shr:1 row_mask:0xf bank_mask:0xf
	v_fmac_f32_dpp v31, v15, v99 row_shr:1 row_mask:0xf bank_mask:0xf
	v_fmac_f32_dpp v25, v9, v113 row_shr:1 row_mask:0xf bank_mask:0xf
	v_fmac_f32_dpp v27, v11, v115 row_shr:1 row_mask:0xf bank_mask:0xf
	v_fmac_f32_dpp v29, v13, v105 row_shl:1 row_mask:0xf bank_mask:0xf
	v_fmac_f32_dpp v31, v15, v107 row_shl:1 row_mask:0xf bank_mask:0xf
	v_fmac_f32_dpp v25, v9, v121 row_shl:1 row_mask:0xf bank_mask:0xf
	v_fmac_f32_dpp v27, v11, v123 row_shl:1 row_mask:0xf bank_mask:0xf
	v_fmac_f32_dpp v29, v21, v201 row_ror:1 row_mask:0xf bank_mask:0xf
	v_fmac_f32_dpp v31, v23, v203 row_ror:1 row_mask:0xf bank_mask:0xf
	v_fmac_f32_dpp v25, v17, v209 row_ror:1 row_mask:0xf bank_mask:0xf
	v_fmac_f32_dpp v27, v19, v211 row_ror:1 row_mask:0xf bank_mask:0xf
	v_fmac_f32_dpp v29, v5, v205 row_ror:15 row_mask:0xf bank_mask:0xf
	v_fmac_f32_dpp v31, v7, v207 row_ror:15 row_mask:0xf bank_mask:0xf
	v_fmac_f32_dpp v25, v1, v213 row_ror:15 row_mask:0xf bank_mask:0xf
	v_fmac_f32_dpp v27, v3, v215 row_ror:15 row_mask:0xf bank_mask:0xf
; DI unsigned cvtpk(float lo, float hi) { unsigned r; asm volatile("v_cvt_pk_bf16_f32 %0, %1, %2" : "=v"(r) : "v"(lo), "v"(hi)); return r; }
;     DI void operator()(const f32x4 (&acc)[2][2][4][2], const Unit& u, int wr, int wc, int fr_, int fq_) const {
;     ...
;                 for (int m = 0; m < 4; ++m) { f32x4 zv, zg;
;                     CONV_ONE(acc, ai, 0, n, m, zv, vp, vm, vn); CONV_ONE(acc, ai, 1, n, m, zg, gp, gm, gn);
;                     zv = zv + vb; zg = zg + gb;
;                     float ov[4];
; #pragma unroll
;                     for (int e = 0; e < 4; ++e) { const float x = zg[e]; const float uu = 1.5957691216f * (x + 0.044715f * x * x * x);
;                         ov[e] = zv[e] * x * __builtin_amdgcn_rcpf(1.f + __expf(-uu)); }
;                     if (ROW_VALID(m)) { const int t = tok0 + 16 * m + fr; u32x2 w; w.x = cvtpk(ov[0], ov[1]); w.y = cvtpk(ov[2], ov[3]);
;                         *(u32x2*)(ACT + (size_t)t * FF + cv0 + 4 * n) = w; }
;                     __builtin_amdgcn_sched_barrier(0); }
;             }
;         }
;     }
	v_pk_fma_f32 v[20:21], v[4:5], v[100:101], v[108:109]
	v_pk_fma_f32 v[22:23], v[6:7], v[102:103], v[110:111]
	v_pk_fma_f32 v[16:17], v[0:1], v[116:117], v[124:125]
	v_pk_fma_f32 v[18:19], v[2:3], v[118:119], v[126:127]
	v_fmac_f32_dpp v20, v4, v96 row_shr:1 row_mask:0xf bank_mask:0xf
	v_fmac_f32_dpp v22, v6, v98 row_shr:1 row_mask:0xf bank_mask:0xf
	v_fmac_f32_dpp v16, v0, v112 row_shr:1 row_mask:0xf bank_mask:0xf
	v_fmac_f32_dpp v18, v2, v114 row_shr:1 row_mask:0xf bank_mask:0xf
	v_fmac_f32_dpp v20, v4, v104 row_shl:1 row_mask:0xf bank_mask:0xf
	v_fmac_f32_dpp v22, v6, v106 row_shl:1 row_mask:0xf bank_mask:0xf
	v_fmac_f32_dpp v16, v0, v120 row_shl:1 row_mask:0xf bank_mask:0xf
	v_fmac_f32_dpp v18, v2, v122 row_shl:1 row_mask:0xf bank_mask:0xf
	v_fmac_f32_dpp v20, v12, v200 row_ror:1 row_mask:0xf bank_mask:0xf
	v_fmac_f32_dpp v22, v14, v202 row_ror:1 row_mask:0xf bank_mask:0xf
	v_fmac_f32_dpp v16, v8, v208 row_ror:1 row_mask:0xf bank_mask:0xf
	v_fmac_f32_dpp v18, v10, v210 row_ror:1 row_mask:0xf bank_mask:0xf
	v_fmac_f32_dpp v21, v5, v97 row_shr:1 row_mask:0xf bank_mask:0xf
	v_fmac_f32_dpp v23, v7, v99 row_shr:1 row_mask:0xf bank_mask:0xf
	v_fmac_f32_dpp v17, v1, v113 row_shr:1 row_mask:0xf bank_mask:0xf
	v_fmac_f32_dpp v19, v3, v115 row_shr:1 row_mask:0xf bank_mask:0xf
	v_fmac_f32_dpp v21, v5, v105 row_shl:1 row_mask:0xf bank_mask:0xf
	v_fmac_f32_dpp v23, v7, v107 row_shl:1 row_mask:0xf bank_mask:0xf
	v_fmac_f32_dpp v17, v1, v121 row_shl:1 row_mask:0xf bank_mask:0xf
	v_fmac_f32_dpp v19, v3, v123 row_shl:1 row_mask:0xf bank_mask:0xf
	v_fmac_f32_dpp v21, v13, v201 row_ror:1 row_mask:0xf bank_mask:0xf
	v_fmac_f32_dpp v23, v15, v203 row_ror:1 row_mask:0xf bank_mask:0xf
	v_fmac_f32_dpp v17, v9, v209 row_ror:1 row_mask:0xf bank_mask:0xf
	v_fmac_f32_dpp v19, v11, v211 row_ror:1 row_mask:0xf bank_mask:0xf
	v_pk_mul_f32 v[172:173], v[224:225], s[40:41] op_sel_hi:[1,0]
	v_pk_mul_f32 v[174:175], v[228:229], s[40:41] op_sel_hi:[1,0]
	v_pk_mul_f32 v[172:173], v[224:225], v[172:173]
	v_pk_mul_f32 v[174:175], v[228:229], v[174:175]
	v_pk_fma_f32 v[172:173], v[224:225], v[172:173], v[224:225]
	v_pk_fma_f32 v[174:175], v[228:229], v[174:175], v[228:229]
	v_pk_mul_f32 v[172:173], v[172:173], s[42:43] op_sel_hi:[1,0]
	v_pk_mul_f32 v[174:175], v[174:175], s[42:43] op_sel_hi:[1,0]
	v_pk_mul_f32 v[176:177], v[216:217], v[224:225]
	v_pk_mul_f32 v[178:179], v[220:221], v[228:229]
	v_exp_f32_e32 v172, v172
	v_exp_f32_e32 v173, v173
	v_exp_f32_e32 v174, v174
	v_exp_f32_e32 v175, v175
	v_pk_add_f32 v[172:173], v[172:173], s[44:45] op_sel_hi:[1,0]
	v_pk_add_f32 v[174:175], v[174:175], s[44:45] op_sel_hi:[1,0]
	v_rcp_f32_e32 v172, v172
	v_rcp_f32_e32 v173, v173
	v_rcp_f32_e32 v174, v174
	v_rcp_f32_e32 v175, v175
	s_mov_b32 s26, 0xaa800
	v_lshl_add_u64 v[170:171], v[186:187], 0, s[26:27]
	v_pk_mul_f32 v[176:177], v[176:177], v[172:173]
	v_pk_mul_f32 v[178:179], v[178:179], v[174:175]
	s_and_b64 exec, s[28:29], s[14:15]
	v_cvt_pk_bf16_f32 v176, v176, v177
	v_cvt_pk_bf16_f32 v177, v178, v179
	global_store_dwordx2 v[170:171], v[176:177], off offset:8
	s_mov_b64 exec, s[28:29]
	v_pk_mul_f32 v[172:173], v[226:227], s[40:41] op_sel_hi:[1,0]
	v_pk_mul_f32 v[174:175], v[194:195], s[40:41] op_sel_hi:[1,0]
	v_pk_mul_f32 v[172:173], v[226:227], v[172:173]
	v_pk_mul_f32 v[174:175], v[194:195], v[174:175]
	v_pk_fma_f32 v[172:173], v[226:227], v[172:173], v[226:227]
	v_pk_fma_f32 v[174:175], v[194:195], v[174:175], v[194:195]
	v_pk_mul_f32 v[172:173], v[172:173], s[42:43] op_sel_hi:[1,0]
	v_pk_mul_f32 v[174:175], v[174:175], s[42:43] op_sel_hi:[1,0]
	v_pk_mul_f32 v[176:177], v[218:219], v[226:227]
	v_pk_mul_f32 v[178:179], v[222:223], v[194:195]
	v_exp_f32_e32 v172, v172
	v_exp_f32_e32 v173, v173
	v_exp_f32_e32 v174, v174
	v_exp_f32_e32 v175, v175
	v_pk_add_f32 v[172:173], v[172:173], s[44:45] op_sel_hi:[1,0]
	v_pk_add_f32 v[174:175], v[174:175], s[44:45] op_sel_hi:[1,0]
	v_rcp_f32_e32 v172, v172
	v_rcp_f32_e32 v173, v173
	v_rcp_f32_e32 v174, v174
	v_rcp_f32_e32 v175, v175
	s_mov_b32 s26, 0xc0800
	v_lshl_add_u64 v[170:171], v[186:187], 0, s[26:27]
	v_pk_mul_f32 v[176:177], v[176:177], v[172:173]
	v_pk_mul_f32 v[178:179], v[178:179], v[174:175]
	v_cvt_pk_bf16_f32 v176, v176, v177
	v_cvt_pk_bf16_f32 v177, v178, v179
	global_store_dwordx2 v[170:171], v[176:177], off offset:8
	v_pk_mul_f32 v[172:173], v[24:25], s[40:41] op_sel_hi:[1,0]
	v_pk_mul_f32 v[174:175], v[26:27], s[40:41] op_sel_hi:[1,0]
	v_pk_mul_f32 v[172:173], v[24:25], v[172:173]
	v_pk_mul_f32 v[174:175], v[26:27], v[174:175]
	v_pk_fma_f32 v[172:173], v[24:25], v[172:173], v[24:25]
	v_pk_fma_f32 v[174:175], v[26:27], v[174:175], v[26:27]
	v_pk_mul_f32 v[172:173], v[172:173], s[42:43] op_sel_hi:[1,0]
	v_pk_mul_f32 v[174:175], v[174:175], s[42:43] op_sel_hi:[1,0]
	v_pk_mul_f32 v[176:177], v[28:29], v[24:25]
	v_pk_mul_f32 v[178:179], v[30:31], v[26:27]
	v_exp_f32_e32 v172, v172
	v_exp_f32_e32 v173, v173
	v_exp_f32_e32 v174, v174
	v_exp_f32_e32 v175, v175
	v_pk_add_f32 v[172:173], v[172:173], s[44:45] op_sel_hi:[1,0]
	v_pk_add_f32 v[174:175], v[174:175], s[44:45] op_sel_hi:[1,0]
	v_rcp_f32_e32 v172, v172
	v_rcp_f32_e32 v173, v173
	v_rcp_f32_e32 v174, v174
	v_rcp_f32_e32 v175, v175
	s_mov_b32 s26, 0xd6800
	v_lshl_add_u64 v[170:171], v[186:187], 0, s[26:27]
	v_pk_mul_f32 v[176:177], v[176:177], v[172:173]
	v_pk_mul_f32 v[178:179], v[178:179], v[174:175]
	v_cvt_pk_bf16_f32 v176, v176, v177
	v_cvt_pk_bf16_f32 v177, v178, v179
	global_store_dwordx2 v[170:171], v[176:177], off offset:8
	v_pk_mul_f32 v[172:173], v[16:17], s[40:41] op_sel_hi:[1,0]
	v_pk_mul_f32 v[174:175], v[18:19], s[40:41] op_sel_hi:[1,0]
	v_pk_mul_f32 v[172:173], v[16:17], v[172:173]
	v_pk_mul_f32 v[174:175], v[18:19], v[174:175]
	v_pk_fma_f32 v[172:173], v[16:17], v[172:173], v[16:17]
	v_pk_fma_f32 v[174:175], v[18:19], v[174:175], v[18:19]
	v_pk_mul_f32 v[172:173], v[172:173], s[42:43] op_sel_hi:[1,0]
	v_pk_mul_f32 v[174:175], v[174:175], s[42:43] op_sel_hi:[1,0]
	v_pk_mul_f32 v[176:177], v[20:21], v[16:17]
	v_pk_mul_f32 v[178:179], v[22:23], v[18:19]
	v_exp_f32_e32 v172, v172
	v_exp_f32_e32 v173, v173
	v_exp_f32_e32 v174, v174
	v_exp_f32_e32 v175, v175
	v_pk_add_f32 v[172:173], v[172:173], s[44:45] op_sel_hi:[1,0]
	v_pk_add_f32 v[174:175], v[174:175], s[44:45] op_sel_hi:[1,0]
	v_rcp_f32_e32 v172, v172
	v_rcp_f32_e32 v173, v173
	v_rcp_f32_e32 v174, v174
	v_rcp_f32_e32 v175, v175
	s_mov_b32 s26, 0xec800
	v_lshl_add_u64 v[170:171], v[186:187], 0, s[26:27]
	v_pk_mul_f32 v[176:177], v[176:177], v[172:173]
	v_pk_mul_f32 v[178:179], v[178:179], v[174:175]
	s_and_b64 exec, s[28:29], s[24:25]
	v_cvt_pk_bf16_f32 v176, v176, v177
	v_cvt_pk_bf16_f32 v177, v178, v179
	global_store_dwordx2 v[170:171], v[176:177], off offset:8
	s_mov_b64 exec, s[28:29]
	s_mov_b64 exec, s[28:29]
	s_movk_i32 s65, 0x2000
	s_mov_b32 s93, 0x1c000
	s_branch .Lup_done
